# EpiUp (UP0/UP1): conv-halo row load issued with the row-statistics load batch (one memory round trip fewer per half-tile), K-loop placement kept
# baseline (speedup 1.0000x reference)
.LBB0_974:
	v_lshl_add_u32 v204, s72, 8, v234
	v_ashrrev_i32_e32 v205, 31, v204
	v_or_b32_e32 v136, 16, v204
	v_lshlrev_b64 v[120:121], 6, v[204:205]
	v_ashrrev_i32_e32 v137, 31, v136
	v_or_b32_e32 v138, 32, v204
	v_lshl_add_u64 v[120:121], v[188:189], 0, v[120:121]
	v_lshlrev_b64 v[122:123], 6, v[136:137]
	v_ashrrev_i32_e32 v139, 31, v138
	v_lshl_add_u64 v[122:123], v[188:189], 0, v[122:123]
	global_load_dwordx4 v[142:145], v[120:121], off
	global_load_dwordx4 v[146:149], v[122:123], off
	v_lshlrev_b64 v[120:121], 6, v[138:139]
	v_or_b32_e32 v140, 48, v204
	v_lshl_add_u64 v[120:121], v[188:189], 0, v[120:121]
	v_ashrrev_i32_e32 v141, 31, v140
	global_load_dwordx4 v[156:159], v[120:121], off
	v_lshlrev_b64 v[120:121], 6, v[140:141]
	v_lshl_add_u64 v[120:121], v[188:189], 0, v[120:121]
	global_load_dwordx4 v[160:163], v[120:121], off
	v_lshl_or_b32 v198, s71, 8, v236
	v_ashrrev_i32_e32 v199, 31, v198
	v_lshl_add_u64 v[206:207], v[198:199], 1, s[12:13]
	v_mad_i64_i32 v[120:121], s[4:5], v204, s70, v[206:207]
	v_mad_i64_i32 v[122:123], s[4:5], v136, s70, v[206:207]
	v_mad_i64_i32 v[128:129], s[4:5], v138, s70, v[206:207]
	v_mad_i64_i32 v[150:151], s[4:5], v140, s70, v[206:207]
	global_load_dwordx4 v[172:175], v[120:121], off
	global_load_dwordx4 v[152:155], v[122:123], off
	s_nop 0
	global_load_dwordx4 v[128:131], v[128:129], off
	s_nop 0
	global_load_dwordx4 v[120:123], v[150:151], off
	v_and_b32_e32 v139, 64, v240
	v_xor_b32_e32 v137, 16, v240
	v_add_u32_e32 v139, 64, v139
	v_cmp_lt_i32_e32 vcc, v137, v139
	v_xor_b32_e32 v141, 32, v240
	v_and_b32_e32 v213, 0x1fcf, v204
	v_cndmask_b32_e32 v137, v240, v137, vcc
	v_lshlrev_b32_e32 v205, 2, v137
	v_cmp_lt_i32_e32 vcc, v141, v139
	v_mul_hi_u32_u24_e32 v221, 0x2c00, v213
	v_mul_u32_u24_e32 v220, 0x2c00, v213
	v_cndmask_b32_e32 v137, v240, v141, vcc
	v_lshlrev_b32_e32 v242, 2, v137
	v_cmp_gt_u32_e32 vcc, 16, v213
	v_add_u32_e32 v179, -16, v204
	v_cndmask_b32_e64 v179, v204, v179, s[0:1]
	v_mad_i64_i32 v[222:223], s[4:5], v179, s70, 0
	v_lshl_add_u64 v[222:223], s[12:13], 0, v[222:223]
	v_lshl_add_u64 v[222:223], v[198:199], 1, v[222:223]
	v_and_b32_e32 v179, 0x1fcf, v204
	v_cmp_le_u32_e64 s[4:5], 16, v179
	s_mov_b64 s[6:7], exec
	s_nop 0
	s_and_b64 exec, exec, s[4:5]
	global_load_dwordx4 v[176:179], v[222:223], off
	s_mov_b64 exec, s[6:7]
	s_waitcnt vmcnt(0)
	v_mov_b32_e32 v150, v143
	v_mov_b32_e32 v151, v144
	v_mov_b32_e32 v143, v145
	v_pk_add_f32 v[142:143], v[150:151], v[142:143]
	v_mov_b32_e32 v144, v147
	v_mov_b32_e32 v145, v148
	v_mov_b32_e32 v147, v149
	v_mov_b32_e32 v148, v157
	v_mov_b32_e32 v149, v158
	v_mov_b32_e32 v157, v159
	v_mov_b32_e32 v150, v161
	v_mov_b32_e32 v151, v162
	v_mov_b32_e32 v161, v163
	v_pk_add_f32 v[144:145], v[144:145], v[146:147]
	v_pk_add_f32 v[148:149], v[148:149], v[156:157]
	v_pk_add_f32 v[150:151], v[150:151], v[160:161]
	v_mov_b32_e32 v147, v142
	v_mov_b32_e32 v146, v144
	v_mov_b32_e32 v142, v145
	v_mov_b32_e32 v144, v150
	v_mov_b32_e32 v145, v148
	v_mov_b32_e32 v148, v151
	v_pk_add_f32 v[142:143], v[146:147], v[142:143]
	v_pk_add_f32 v[144:145], v[144:145], v[148:149]
	ds_bpermute_b32 v147, v205, v143
	ds_bpermute_b32 v146, v205, v142
	ds_bpermute_b32 v149, v205, v145
	ds_bpermute_b32 v148, v205, v144
	s_waitcnt lgkmcnt(2)
	v_pk_add_f32 v[146:147], v[142:143], v[146:147]
	s_waitcnt lgkmcnt(0)
	v_pk_add_f32 v[142:143], v[144:145], v[148:149]
	ds_bpermute_b32 v149, v242, v147
	ds_bpermute_b32 v148, v242, v146
	ds_bpermute_b32 v145, v242, v143
	ds_bpermute_b32 v144, v242, v142
	s_and_saveexec_b64 s[4:5], vcc
	s_xor_b64 s[6:7], exec, s[4:5]
	s_cbranch_execz .LBB0_978
	v_mov_b32_e32 v179, 0
	v_mov_b32_e32 v178, 0
	v_mov_b32_e32 v177, 0
	v_mov_b32_e32 v176, 0
	s_and_saveexec_b64 s[82:83], s[0:1]
	s_cbranch_execz .LBB0_977
	v_readlane_b32 s4, v254, 11
	v_lshlrev_b32_e32 v137, 2, v213
	v_readlane_b32 s5, v254, 12
	s_nop 4
	global_load_dword v137, v137, s[4:5]
	v_readlane_b32 s4, v254, 19
	v_readlane_b32 s5, v254, 20
	s_waitcnt vmcnt(0)
	v_fmamk_f32 v137, v137, 0x3a800000, v241
	v_lshl_add_u64 v[150:151], s[4:5], 0, v[220:221]
	v_lshl_add_u64 v[150:151], v[198:199], 2, v[150:151]
	global_load_dwordx4 v[156:159], v[150:151], off
	global_load_dwordx4 v[160:163], v[150:151], off offset:16
	v_mul_f32_e32 v139, 0x4b800000, v137
	v_cmp_gt_f32_e64 s[4:5], s77, v137
	s_nop 1
	v_cndmask_b32_e64 v137, v137, v139, s[4:5]
	v_rsq_f32_e32 v137, v137
	s_nop 0
	v_mul_f32_e32 v139, 0x45800000, v137
	v_cndmask_b32_e64 v150, v137, v139, s[4:5]
	s_waitcnt vmcnt(1)
	v_pk_mul_f32 v[156:157], v[156:157], v[150:151] op_sel_hi:[1,0]
	v_pk_mul_f32 v[158:159], v[158:159], v[150:151] op_sel_hi:[1,0]
	s_waitcnt vmcnt(0)
	v_pk_mul_f32 v[160:161], v[160:161], v[150:151] op_sel_hi:[1,0]
	v_pk_mul_f32 v[150:151], v[150:151], v[162:163] op_sel_hi:[0,1]
	v_cvt_pk_bf16_f32 v176, v156, v157
	v_cvt_pk_bf16_f32 v177, v158, v159
	v_cvt_pk_bf16_f32 v178, v160, v161
	v_cvt_pk_bf16_f32 v179, v150, v151

.LBB0_978:
	s_or_saveexec_b64 s[4:5], s[6:7]
	v_add_u32_e32 v137, -16, v204
	v_cndmask_b32_e64 v137, v204, v137, s[0:1]
	v_mad_i64_i32 v[150:151], s[6:7], v137, s70, 0
	v_lshl_add_u64 v[150:151], s[12:13], 0, v[150:151]
	v_lshl_add_u64 v[222:223], v[198:199], 1, v[150:151]
	s_xor_b64 exec, exec, s[4:5]
	s_cbranch_execz .LBB0_980


.LBB0_986:
	s_or_b64 exec, exec, s[4:5]
	global_load_dwordx4 v[104:107], v[200:201], off offset:528
	global_load_dwordx4 v[120:123], v[200:201], off offset:512
	global_load_dwordx4 v[108:111], v[202:203], off offset:528
	global_load_dwordx4 v[132:135], v[202:203], off offset:512
	v_lshlrev_b64 v[116:117], 2, v[112:113]
	v_lshl_add_u64 v[150:151], s[38:39], 0, v[116:117]
	global_load_dwordx4 v[128:131], v[150:151], off
	global_load_dwordx4 v[112:115], v[150:151], off offset:16
	v_lshl_add_u64 v[152:153], s[44:45], 0, v[116:117]
	global_load_dwordx4 v[124:127], v[152:153], off
	global_load_dwordx4 v[116:119], v[152:153], off offset:16
	s_nop 0
	s_nop 0
	s_nop 0
	s_nop 0
	s_nop 0
	s_waitcnt vmcnt(8)
	v_mov_b32_dpp v164, v144 row_ror:1 row_mask:0xf bank_mask:0xf
	v_mov_b32_dpp v165, v144 row_ror:2 row_mask:0xf bank_mask:0xf
	v_mov_b32_dpp v167, v145 row_ror:1 row_mask:0xf bank_mask:0xf
	v_mov_b32_dpp v168, v145 row_ror:2 row_mask:0xf bank_mask:0xf
	v_mov_b32_e32 v219, v218
	s_nop 0
	s_nop 0
	s_nop 0
	v_mov_b32_dpp v171, v146 row_ror:2 row_mask:0xf bank_mask:0xf
	v_mov_b32_dpp v164, v140 row_shr:1 row_mask:0xf bank_mask:0xf
	v_mov_b32_dpp v165, v140 row_shr:2 row_mask:0xf bank_mask:0xf
	v_mov_b32_dpp v167, v141 row_shr:1 row_mask:0xf bank_mask:0xf
	v_mov_b32_dpp v168, v141 row_shr:2 row_mask:0xf bank_mask:0xf
	v_mov_b32_dpp v169, v146 row_ror:1 row_mask:0xf bank_mask:0xf
	v_mov_b32_dpp v174, v147 row_ror:1 row_mask:0xf bank_mask:0xf
	v_mov_b32_dpp v175, v147 row_ror:2 row_mask:0xf bank_mask:0xf
	v_pk_mul_f32 v[144:145], v[88:89], v[218:219]
	v_mov_b32_dpp v171, v142 row_shr:2 row_mask:0xf bank_mask:0xf
	v_lshlrev_b32_e32 v88, 16, v164
	v_lshlrev_b32_e32 v146, 16, v165
	v_and_b32_e32 v89, 0xffff0000, v164
	v_and_b32_e32 v147, 0xffff0000, v165
	v_lshlrev_b32_e32 v164, 16, v167
	v_lshlrev_b32_e32 v166, 16, v168
	v_and_b32_e32 v165, 0xffff0000, v167
	v_and_b32_e32 v167, 0xffff0000, v168
	v_mov_b32_dpp v169, v142 row_shr:1 row_mask:0xf bank_mask:0xf
	v_lshlrev_b32_e32 v170, 16, v171
	v_and_b32_e32 v171, 0xffff0000, v171
	v_lshlrev_b32_e32 v158, 16, v140
	v_and_b32_e32 v159, 0xffff0000, v140
	v_lshlrev_b32_e32 v160, 16, v141
	v_and_b32_e32 v161, 0xffff0000, v141
	v_lshlrev_b32_e32 v168, 16, v169
	v_and_b32_e32 v169, 0xffff0000, v169
	v_lshlrev_b32_e32 v162, 16, v142
	v_and_b32_e32 v163, 0xffff0000, v142
	v_pk_mul_f32 v[92:93], v[92:93], v[218:219]
	v_pk_mul_f32 v[94:95], v[94:95], v[218:219]
	v_mov_b32_dpp v175, v143 row_shr:2 row_mask:0xf bank_mask:0xf
	v_mov_b32_dpp v174, v143 row_shr:1 row_mask:0xf bank_mask:0xf
	v_pk_mul_f32 v[90:91], v[90:91], v[218:219]
	v_mov_b32_e32 v217, v216
	v_pk_mul_f32 v[84:85], v[84:85], v[216:217]
	v_pk_mul_f32 v[86:87], v[86:87], v[216:217]
	v_pk_mul_f32 v[80:81], v[80:81], v[216:217]
	v_pk_mul_f32 v[82:83], v[82:83], v[216:217]
	v_mov_b32_e32 v215, v214
	v_pk_mul_f32 v[76:77], v[76:77], v[214:215]
	v_pk_mul_f32 v[78:79], v[78:79], v[214:215]
	v_pk_mul_f32 v[72:73], v[72:73], v[214:215]
	v_pk_mul_f32 v[74:75], v[74:75], v[214:215]
	v_mov_b32_e32 v213, v212
	v_pk_mul_f32 v[68:69], v[68:69], v[212:213]
	v_pk_mul_f32 v[70:71], v[70:71], v[212:213]
	v_pk_mul_f32 v[64:65], v[64:65], v[212:213]
	v_pk_mul_f32 v[66:67], v[66:67], v[212:213]
	s_waitcnt vmcnt(5)
	v_pk_fma_f32 v[170:171], v[104:105], v[170:171], v[108:109]
	s_waitcnt vmcnt(4)
	v_pk_fma_f32 v[146:147], v[120:121], v[146:147], v[132:133]
	v_pk_fma_f32 v[166:167], v[122:123], v[166:167], v[134:135]
	s_waitcnt vmcnt(3)
	v_pk_fma_f32 v[88:89], v[128:129], v[88:89], v[146:147]
	v_pk_fma_f32 v[146:147], v[130:131], v[164:165], v[166:167]
	s_waitcnt vmcnt(2)
	v_pk_fma_f32 v[164:165], v[112:113], v[168:169], v[170:171]
	s_waitcnt vmcnt(1)
	v_pk_fma_f32 v[88:89], v[124:125], v[158:159], v[88:89]
	v_pk_fma_f32 v[146:147], v[126:127], v[160:161], v[146:147]
	s_waitcnt vmcnt(0)
	v_pk_fma_f32 v[158:159], v[116:117], v[162:163], v[164:165]
	v_mul_f32_e32 v160, 0xbfb8aa3b, v88
	v_mul_f32_e32 v161, 0xbfb8aa3b, v89
	v_mul_f32_e32 v162, 0xbfb8aa3b, v146
	v_mul_f32_e32 v163, 0xbfb8aa3b, v147
	v_exp_f32_e32 v160, v160
	v_exp_f32_e32 v161, v161
	v_exp_f32_e32 v162, v162
	v_exp_f32_e32 v163, v163
	v_add_f32_e32 v160, 1.0, v160
	v_add_f32_e32 v161, 1.0, v161
	v_add_f32_e32 v162, 1.0, v162
	v_add_f32_e32 v163, 1.0, v163
	v_rcp_f32_e32 v160, v160
	v_rcp_f32_e32 v161, v161
	v_rcp_f32_e32 v162, v162
	v_rcp_f32_e32 v163, v163
	v_mul_f32_e32 v164, 0xbfb8aa3b, v158
	v_pk_mul_f32 v[88:89], v[88:89], v[160:161]
	v_mul_f32_e32 v165, 0xbfb8aa3b, v159
	v_pk_mul_f32 v[146:147], v[146:147], v[162:163]
	v_pk_mul_f32 v[88:89], v[92:93], v[88:89]
	v_pk_mul_f32 v[92:93], v[94:95], v[146:147]
	v_lshlrev_b32_e32 v94, 16, v175
	v_and_b32_e32 v95, 0xffff0000, v175
	v_cvt_pk_bf16_f32 v88, v88, v89
	v_cvt_pk_bf16_f32 v89, v92, v93
	v_lshlrev_b32_e32 v92, 16, v174
	v_and_b32_e32 v93, 0xffff0000, v174
	v_pk_fma_f32 v[94:95], v[106:107], v[94:95], v[110:111]
	v_lshlrev_b32_e32 v146, 16, v143
	v_and_b32_e32 v147, 0xffff0000, v143
	v_pk_fma_f32 v[92:93], v[114:115], v[92:93], v[94:95]
	v_exp_f32_e32 v164, v164
	v_pk_fma_f32 v[92:93], v[118:119], v[146:147], v[92:93]
	v_exp_f32_e32 v165, v165
	v_mul_f32_e32 v94, 0xbfb8aa3b, v92
	v_mul_f32_e32 v95, 0xbfb8aa3b, v93
	v_exp_f32_e32 v94, v94
	v_exp_f32_e32 v95, v95
	v_add_f32_e32 v164, 1.0, v164
	v_add_f32_e32 v160, 1.0, v165
	v_add_f32_e32 v94, 1.0, v94
	v_add_f32_e32 v95, 1.0, v95
	v_rcp_f32_e32 v164, v164
	v_rcp_f32_e32 v165, v160
	v_rcp_f32_e32 v94, v94
	v_rcp_f32_e32 v95, v95
	v_pk_mul_f32 v[146:147], v[158:159], v[164:165]
	s_nop 0
	v_pk_mul_f32 v[144:145], v[144:145], v[146:147]
	v_pk_mul_f32 v[92:93], v[92:93], v[94:95]
	s_nop 0
	v_pk_mul_f32 v[92:93], v[90:91], v[92:93]
	v_cvt_pk_bf16_f32 v90, v144, v145
	v_cvt_pk_bf16_f32 v91, v92, v93
	global_store_dwordx4 v[178:179], v[88:91], off offset:256
	v_mov_b32_dpp v95, v141 row_ror:1 row_mask:0xf bank_mask:0xf
	v_lshlrev_b32_e32 v92, 16, v136
	s_nop 0
	s_nop 0
	v_mov_b32_dpp v95, v137 row_shr:1 row_mask:0xf bank_mask:0xf
	v_mov_b32_dpp v91, v140 row_ror:2 row_mask:0xf bank_mask:0xf
	v_mov_b32_dpp v89, v140 row_ror:1 row_mask:0xf bank_mask:0xf
	s_nop 0
	v_mov_b32_dpp v91, v136 row_shr:2 row_mask:0xf bank_mask:0xf
	v_mov_b32_dpp v89, v136 row_shr:1 row_mask:0xf bank_mask:0xf
	v_lshlrev_b32_e32 v90, 16, v91
	v_and_b32_e32 v91, 0xffff0000, v91
	v_mov_b32_dpp v140, v141 row_ror:2 row_mask:0xf bank_mask:0xf
	v_lshlrev_b32_e32 v88, 16, v89
	v_and_b32_e32 v89, 0xffff0000, v89
	v_pk_fma_f32 v[90:91], v[120:121], v[90:91], v[132:133]
	v_and_b32_e32 v93, 0xffff0000, v136
	v_pk_fma_f32 v[88:89], v[128:129], v[88:89], v[90:91]
	v_mov_b32_dpp v140, v137 row_shr:2 row_mask:0xf bank_mask:0xf
	v_pk_fma_f32 v[88:89], v[124:125], v[92:93], v[88:89]
	v_lshlrev_b32_e32 v92, 16, v95
	v_lshlrev_b32_e32 v94, 16, v140
	v_and_b32_e32 v93, 0xffff0000, v95
	v_and_b32_e32 v95, 0xffff0000, v140
	v_pk_fma_f32 v[94:95], v[122:123], v[94:95], v[134:135]
	v_lshlrev_b32_e32 v140, 16, v137
	v_and_b32_e32 v141, 0xffff0000, v137
	v_pk_fma_f32 v[92:93], v[130:131], v[92:93], v[94:95]
	v_mul_f32_e32 v90, 0xbfb8aa3b, v88
	v_mul_f32_e32 v91, 0xbfb8aa3b, v89
	v_pk_fma_f32 v[92:93], v[126:127], v[140:141], v[92:93]
	v_exp_f32_e32 v90, v90
	v_exp_f32_e32 v91, v91
	v_mul_f32_e32 v94, 0xbfb8aa3b, v92
	v_mul_f32_e32 v95, 0xbfb8aa3b, v93
	v_exp_f32_e32 v94, v94
	v_exp_f32_e32 v95, v95
	v_add_f32_e32 v90, 1.0, v90
	v_add_f32_e32 v91, 1.0, v91
	v_rcp_f32_e32 v90, v90
	v_rcp_f32_e32 v91, v91
	v_add_f32_e32 v94, 1.0, v94
	v_add_f32_e32 v95, 1.0, v95
	v_rcp_f32_e32 v94, v94
	v_rcp_f32_e32 v95, v95
	v_pk_mul_f32 v[88:89], v[88:89], v[90:91]
	v_lshlrev_b32_e32 v90, 16, v138
	v_pk_mul_f32 v[84:85], v[84:85], v[88:89]
	v_pk_mul_f32 v[88:89], v[92:93], v[94:95]
	v_cvt_pk_bf16_f32 v84, v84, v85
	v_pk_mul_f32 v[86:87], v[86:87], v[88:89]
	s_nop 0
	v_cvt_pk_bf16_f32 v85, v86, v87
	s_nop 0
	v_mov_b32_dpp v89, v142 row_ror:2 row_mask:0xf bank_mask:0xf
	s_nop 0
	v_mov_b32_dpp v87, v142 row_ror:1 row_mask:0xf bank_mask:0xf
	v_mov_b32_dpp v89, v138 row_shr:2 row_mask:0xf bank_mask:0xf
	s_nop 0
	v_mov_b32_dpp v87, v138 row_shr:1 row_mask:0xf bank_mask:0xf
	v_lshlrev_b32_e32 v88, 16, v89
	v_and_b32_e32 v89, 0xffff0000, v89
	v_mov_b32_dpp v93, v143 row_ror:1 row_mask:0xf bank_mask:0xf
	v_mov_b32_dpp v94, v143 row_ror:2 row_mask:0xf bank_mask:0xf
	v_lshlrev_b32_e32 v86, 16, v87
	v_and_b32_e32 v87, 0xffff0000, v87
	v_pk_fma_f32 v[88:89], v[104:105], v[88:89], v[108:109]
	v_mov_b32_dpp v93, v139 row_shr:1 row_mask:0xf bank_mask:0xf
	v_and_b32_e32 v91, 0xffff0000, v138
	v_pk_fma_f32 v[86:87], v[112:113], v[86:87], v[88:89]
	v_mov_b32_dpp v94, v139 row_shr:2 row_mask:0xf bank_mask:0xf
	v_pk_fma_f32 v[86:87], v[116:117], v[90:91], v[86:87]
	v_lshlrev_b32_e32 v90, 16, v93
	v_lshlrev_b32_e32 v92, 16, v94
	v_and_b32_e32 v91, 0xffff0000, v93
	v_and_b32_e32 v93, 0xffff0000, v94
	v_pk_fma_f32 v[92:93], v[106:107], v[92:93], v[110:111]
	v_lshlrev_b32_e32 v94, 16, v139
	v_and_b32_e32 v95, 0xffff0000, v139
	v_pk_fma_f32 v[90:91], v[114:115], v[90:91], v[92:93]
	v_mul_f32_e32 v88, 0xbfb8aa3b, v86
	v_mul_f32_e32 v89, 0xbfb8aa3b, v87
	v_pk_fma_f32 v[90:91], v[118:119], v[94:95], v[90:91]
	v_exp_f32_e32 v88, v88
	v_exp_f32_e32 v89, v89
	v_mul_f32_e32 v92, 0xbfb8aa3b, v90
	v_mul_f32_e32 v93, 0xbfb8aa3b, v91
	v_exp_f32_e32 v92, v92
	v_exp_f32_e32 v93, v93
	v_add_f32_e32 v88, 1.0, v88
	v_add_f32_e32 v89, 1.0, v89
	v_rcp_f32_e32 v88, v88
	v_rcp_f32_e32 v89, v89
	v_add_f32_e32 v92, 1.0, v92
	v_add_f32_e32 v93, 1.0, v93
	v_rcp_f32_e32 v92, v92
	v_rcp_f32_e32 v93, v93
	v_pk_mul_f32 v[86:87], v[86:87], v[88:89]
	s_nop 0
	v_pk_mul_f32 v[80:81], v[80:81], v[86:87]
	v_pk_mul_f32 v[86:87], v[90:91], v[92:93]
	v_mov_b32_dpp v88, v137 row_ror:2 row_mask:0xf bank_mask:0xf
	v_pk_mul_f32 v[82:83], v[82:83], v[86:87]
	v_cvt_pk_bf16_f32 v86, v80, v81
	v_cvt_pk_bf16_f32 v87, v82, v83
	s_nop 0
	s_nop 0
	global_store_dwordx4 v[172:173], v[84:87], off offset:256
	v_mov_b32_dpp v83, v136 row_ror:2 row_mask:0xf bank_mask:0xf
	v_mov_b32_dpp v81, v136 row_ror:1 row_mask:0xf bank_mask:0xf
	s_nop 0
	v_mov_b32_dpp v83, v100 row_shr:2 row_mask:0xf bank_mask:0xf
	v_mov_b32_dpp v81, v100 row_shr:1 row_mask:0xf bank_mask:0xf
	v_lshlrev_b32_e32 v82, 16, v83
	v_and_b32_e32 v83, 0xffff0000, v83
	v_mov_b32_dpp v87, v137 row_ror:1 row_mask:0xf bank_mask:0xf
	v_lshlrev_b32_e32 v80, 16, v81
	v_and_b32_e32 v81, 0xffff0000, v81
	v_pk_fma_f32 v[82:83], v[120:121], v[82:83], v[132:133]
	v_mov_b32_dpp v87, v101 row_shr:1 row_mask:0xf bank_mask:0xf
	v_lshlrev_b32_e32 v84, 16, v100
	v_and_b32_e32 v85, 0xffff0000, v100
	v_pk_fma_f32 v[80:81], v[128:129], v[80:81], v[82:83]
	v_mov_b32_dpp v88, v101 row_shr:2 row_mask:0xf bank_mask:0xf
	v_pk_fma_f32 v[80:81], v[124:125], v[84:85], v[80:81]
	v_lshlrev_b32_e32 v84, 16, v87
	v_lshlrev_b32_e32 v86, 16, v88
	v_and_b32_e32 v85, 0xffff0000, v87
	v_and_b32_e32 v87, 0xffff0000, v88
	v_pk_fma_f32 v[86:87], v[122:123], v[86:87], v[134:135]
	v_lshlrev_b32_e32 v88, 16, v101
	v_and_b32_e32 v89, 0xffff0000, v101
	v_pk_fma_f32 v[84:85], v[130:131], v[84:85], v[86:87]
	v_mul_f32_e32 v82, 0xbfb8aa3b, v80
	v_mul_f32_e32 v83, 0xbfb8aa3b, v81
	v_pk_fma_f32 v[84:85], v[126:127], v[88:89], v[84:85]
	v_exp_f32_e32 v82, v82
	v_exp_f32_e32 v83, v83
	v_mul_f32_e32 v86, 0xbfb8aa3b, v84
	v_mul_f32_e32 v87, 0xbfb8aa3b, v85
	v_exp_f32_e32 v86, v86
	v_exp_f32_e32 v87, v87
	v_add_f32_e32 v82, 1.0, v82
	v_add_f32_e32 v83, 1.0, v83
	v_rcp_f32_e32 v82, v82
	v_rcp_f32_e32 v83, v83
	v_add_f32_e32 v86, 1.0, v86
	v_add_f32_e32 v87, 1.0, v87
	v_rcp_f32_e32 v86, v86
	v_rcp_f32_e32 v87, v87
	v_pk_mul_f32 v[80:81], v[80:81], v[82:83]
	v_lshlrev_b32_e32 v82, 16, v102
	v_pk_mul_f32 v[76:77], v[76:77], v[80:81]
	v_pk_mul_f32 v[80:81], v[84:85], v[86:87]
	v_cvt_pk_bf16_f32 v76, v76, v77
	v_pk_mul_f32 v[78:79], v[78:79], v[80:81]
	s_nop 0
	v_cvt_pk_bf16_f32 v77, v78, v79
	s_nop 0
	v_mov_b32_dpp v81, v138 row_ror:2 row_mask:0xf bank_mask:0xf
	s_nop 0
	v_mov_b32_dpp v79, v138 row_ror:1 row_mask:0xf bank_mask:0xf
	v_mov_b32_dpp v81, v102 row_shr:2 row_mask:0xf bank_mask:0xf
	s_nop 0
	v_mov_b32_dpp v79, v102 row_shr:1 row_mask:0xf bank_mask:0xf
	v_lshlrev_b32_e32 v80, 16, v81
	v_and_b32_e32 v81, 0xffff0000, v81
	v_mov_b32_dpp v85, v139 row_ror:1 row_mask:0xf bank_mask:0xf
	v_mov_b32_dpp v86, v139 row_ror:2 row_mask:0xf bank_mask:0xf
	v_lshlrev_b32_e32 v78, 16, v79
	v_and_b32_e32 v79, 0xffff0000, v79
	v_pk_fma_f32 v[80:81], v[104:105], v[80:81], v[108:109]
	v_mov_b32_dpp v85, v103 row_shr:1 row_mask:0xf bank_mask:0xf
	v_and_b32_e32 v83, 0xffff0000, v102
	v_pk_fma_f32 v[78:79], v[112:113], v[78:79], v[80:81]
	v_mov_b32_dpp v86, v103 row_shr:2 row_mask:0xf bank_mask:0xf
	v_pk_fma_f32 v[78:79], v[116:117], v[82:83], v[78:79]
	v_lshlrev_b32_e32 v82, 16, v85
	v_lshlrev_b32_e32 v84, 16, v86
	v_and_b32_e32 v83, 0xffff0000, v85
	v_and_b32_e32 v85, 0xffff0000, v86
	v_pk_fma_f32 v[84:85], v[106:107], v[84:85], v[110:111]
	v_lshlrev_b32_e32 v86, 16, v103
	v_and_b32_e32 v87, 0xffff0000, v103
	v_pk_fma_f32 v[82:83], v[114:115], v[82:83], v[84:85]
	v_mul_f32_e32 v80, 0xbfb8aa3b, v78
	v_mul_f32_e32 v81, 0xbfb8aa3b, v79
	v_pk_fma_f32 v[82:83], v[118:119], v[86:87], v[82:83]
	v_exp_f32_e32 v80, v80
	v_exp_f32_e32 v81, v81
	v_mul_f32_e32 v84, 0xbfb8aa3b, v82
	v_mul_f32_e32 v85, 0xbfb8aa3b, v83
	v_exp_f32_e32 v84, v84
	v_exp_f32_e32 v85, v85
	v_add_f32_e32 v80, 1.0, v80
	v_add_f32_e32 v81, 1.0, v81
	v_rcp_f32_e32 v80, v80
	v_rcp_f32_e32 v81, v81
	v_add_f32_e32 v84, 1.0, v84
	v_add_f32_e32 v85, 1.0, v85
	v_rcp_f32_e32 v84, v84
	v_rcp_f32_e32 v85, v85
	v_pk_mul_f32 v[78:79], v[78:79], v[80:81]
	s_nop 0
	v_pk_mul_f32 v[72:73], v[72:73], v[78:79]
	v_pk_mul_f32 v[78:79], v[82:83], v[84:85]
	s_nop 0
	v_pk_mul_f32 v[74:75], v[74:75], v[78:79]
	v_cvt_pk_bf16_f32 v78, v72, v73
	s_nop 0
	v_cvt_pk_bf16_f32 v79, v74, v75
	s_nop 0
	v_mov_b32_dpp v73, v100 row_ror:2 row_mask:0xf bank_mask:0xf
	global_store_dwordx4 v[154:155], v[76:79], off offset:256
	v_mov_b32_dpp v75, v100 row_ror:1 row_mask:0xf bank_mask:0xf
	v_mov_b32_dpp v73, v96 row_shr:2 row_mask:0xf bank_mask:0xf
	v_lshlrev_b32_e32 v72, 16, v73
	v_mov_b32_dpp v75, v96 row_shr:1 row_mask:0xf bank_mask:0xf
	v_and_b32_e32 v73, 0xffff0000, v73
	v_lshlrev_b32_e32 v74, 16, v75
	v_and_b32_e32 v75, 0xffff0000, v75
	v_pk_fma_f32 v[72:73], v[120:121], v[72:73], v[132:133]
	s_nop 0
	v_pk_fma_f32 v[72:73], v[128:129], v[74:75], v[72:73]
	v_lshlrev_b32_e32 v74, 16, v96
	v_and_b32_e32 v75, 0xffff0000, v96
	v_pk_fma_f32 v[72:73], v[124:125], v[74:75], v[72:73]
	s_nop 0
	v_mul_f32_e32 v74, 0xbfb8aa3b, v72
	v_mul_f32_e32 v75, 0xbfb8aa3b, v73
	v_exp_f32_e32 v74, v74
	v_exp_f32_e32 v75, v75
	v_mov_b32_dpp v78, v101 row_ror:2 row_mask:0xf bank_mask:0xf
	v_mov_b32_dpp v76, v101 row_ror:1 row_mask:0xf bank_mask:0xf
	v_add_f32_e32 v74, 1.0, v74
	v_add_f32_e32 v75, 1.0, v75
	v_rcp_f32_e32 v74, v74
	v_rcp_f32_e32 v75, v75
	v_mov_b32_dpp v78, v97 row_shr:2 row_mask:0xf bank_mask:0xf
	v_mov_b32_dpp v76, v97 row_shr:1 row_mask:0xf bank_mask:0xf
	v_lshlrev_b32_e32 v80, 16, v76
	v_pk_mul_f32 v[72:73], v[72:73], v[74:75]
	v_lshlrev_b32_e32 v74, 16, v78
	v_and_b32_e32 v75, 0xffff0000, v78
	v_and_b32_e32 v81, 0xffff0000, v76
	v_pk_fma_f32 v[74:75], v[122:123], v[74:75], v[134:135]
	s_nop 0
	v_pk_fma_f32 v[74:75], v[130:131], v[80:81], v[74:75]
	v_lshlrev_b32_e32 v80, 16, v97
	v_and_b32_e32 v81, 0xffff0000, v97
	v_mov_b32_dpp v84, v102 row_ror:2 row_mask:0xf bank_mask:0xf
	v_pk_fma_f32 v[74:75], v[126:127], v[80:81], v[74:75]
	v_mov_b32_dpp v83, v102 row_ror:1 row_mask:0xf bank_mask:0xf
	v_mov_b32_dpp v84, v98 row_shr:2 row_mask:0xf bank_mask:0xf
	v_mul_f32_e32 v76, 0xbfb8aa3b, v74
	v_mov_b32_dpp v83, v98 row_shr:1 row_mask:0xf bank_mask:0xf
	v_exp_f32_e32 v76, v76
	v_lshlrev_b32_e32 v80, 16, v84
	v_and_b32_e32 v81, 0xffff0000, v84
	v_lshlrev_b32_e32 v82, 16, v83
	v_and_b32_e32 v83, 0xffff0000, v83
	v_pk_fma_f32 v[80:81], v[104:105], v[80:81], v[108:109]
	v_pk_mul_f32 v[68:69], v[68:69], v[72:73]
	v_pk_fma_f32 v[80:81], v[112:113], v[82:83], v[80:81]
	v_lshlrev_b32_e32 v82, 16, v98
	v_and_b32_e32 v83, 0xffff0000, v98
	v_mul_f32_e32 v72, 0xbfb8aa3b, v75
	v_pk_fma_f32 v[80:81], v[116:117], v[82:83], v[80:81]
	v_exp_f32_e32 v73, v72
	v_add_f32_e32 v72, 1.0, v76
	v_mul_f32_e32 v76, 0xbfb8aa3b, v80
	v_exp_f32_e32 v76, v76
	v_mul_f32_e32 v78, 0xbfb8aa3b, v81
	v_exp_f32_e32 v78, v78
	v_add_f32_e32 v73, 1.0, v73
	s_nop 0
	v_mov_b32_dpp v86, v103 row_ror:2 row_mask:0xf bank_mask:0xf
	v_rcp_f32_e32 v72, v72
	v_rcp_f32_e32 v73, v73
	v_add_f32_e32 v76, 1.0, v76
	v_mov_b32_dpp v85, v103 row_ror:1 row_mask:0xf bank_mask:0xf
	v_mov_b32_dpp v86, v99 row_shr:2 row_mask:0xf bank_mask:0xf
	v_rcp_f32_e32 v82, v76
	v_add_f32_e32 v76, 1.0, v78
	v_mov_b32_dpp v85, v99 row_shr:1 row_mask:0xf bank_mask:0xf
	v_and_b32_e32 v77, 0xffff0000, v86
	v_rcp_f32_e32 v83, v76
	v_lshlrev_b32_e32 v76, 16, v86
	v_and_b32_e32 v79, 0xffff0000, v85
	v_lshlrev_b32_e32 v78, 16, v85
	v_pk_fma_f32 v[76:77], v[106:107], v[76:77], v[110:111]
	v_pk_mul_f32 v[72:73], v[74:75], v[72:73]
	v_lshlrev_b32_e32 v74, 16, v99
	v_and_b32_e32 v75, 0xffff0000, v99
	v_pk_fma_f32 v[76:77], v[114:115], v[78:79], v[76:77]
	v_pk_mul_f32 v[70:71], v[70:71], v[72:73]
	v_pk_fma_f32 v[74:75], v[118:119], v[74:75], v[76:77]
	v_pk_mul_f32 v[72:73], v[80:81], v[82:83]
	v_mul_f32_e32 v76, 0xbfb8aa3b, v74
	v_exp_f32_e32 v76, v76
	v_mul_f32_e32 v77, 0xbfb8aa3b, v75
	v_exp_f32_e32 v77, v77
	v_pk_mul_f32 v[72:73], v[64:65], v[72:73]
	v_add_f32_e32 v64, 1.0, v76
	v_rcp_f32_e32 v76, v64
	v_add_f32_e32 v64, 1.0, v77
	v_rcp_f32_e32 v77, v64
	v_cvt_pk_bf16_f32 v64, v68, v69
	v_cvt_pk_bf16_f32 v65, v70, v71
	v_add_u32_e32 v70, 0x90, v204
	v_pk_mul_f32 v[68:69], v[74:75], v[76:77]
	v_ashrrev_i32_e32 v71, 31, v70
	v_pk_mul_f32 v[68:69], v[66:67], v[68:69]
	v_cvt_pk_bf16_f32 v66, v72, v73
	v_cvt_pk_bf16_f32 v67, v68, v69
	v_add_u32_e32 v68, 0x80, v204
	v_ashrrev_i32_e32 v69, 31, v68
	global_store_dwordx4 v[156:157], v[64:67], off offset:256
	v_add_u32_e32 v76, 0xa0, v204
	v_ashrrev_i32_e32 v77, 31, v76
	v_lshlrev_b64 v[64:65], 6, v[68:69]
	v_lshl_add_u64 v[64:65], v[188:189], 0, v[64:65]
	global_load_dwordx4 v[80:83], v[64:65], off
	v_lshlrev_b64 v[64:65], 6, v[70:71]
	v_lshl_add_u64 v[64:65], v[188:189], 0, v[64:65]
	global_load_dwordx4 v[84:87], v[64:65], off
	v_lshlrev_b64 v[64:65], 6, v[76:77]
	v_add_u32_e32 v78, 0xb0, v204
	v_lshl_add_u64 v[64:65], v[188:189], 0, v[64:65]
	v_ashrrev_i32_e32 v79, 31, v78
	global_load_dwordx4 v[92:95], v[64:65], off
	v_lshlrev_b64 v[64:65], 6, v[78:79]
	v_lshl_add_u64 v[64:65], v[188:189], 0, v[64:65]
	global_load_dwordx4 v[96:99], v[64:65], off
	v_mad_i64_i32 v[64:65], s[4:5], v68, s70, v[206:207]
	v_mad_i64_i32 v[66:67], s[4:5], v70, s70, v[206:207]
	global_load_dwordx4 v[108:111], v[64:65], off
	global_load_dwordx4 v[88:91], v[66:67], off
	v_mad_i64_i32 v[64:65], s[4:5], v76, s70, v[206:207]
	v_mad_i64_i32 v[66:67], s[4:5], v78, s70, v[206:207]
	global_load_dwordx4 v[72:75], v[64:65], off
	s_nop 0
	global_load_dwordx4 v[64:67], v[66:67], off
	v_and_b32_e32 v117, 0x1fcf, v68
	v_cmp_gt_u32_e32 vcc, 16, v117
	v_mul_hi_u32_u24_e32 v125, 0x2c00, v117
	v_mul_u32_u24_e32 v124, 0x2c00, v117
	v_add_u32_e32 v115, 0x70, v204
	v_cndmask_b32_e64 v115, v68, v115, s[0:1]
	v_mad_i64_i32 v[126:127], s[4:5], v115, s70, 0
	v_lshl_add_u64 v[126:127], s[12:13], 0, v[126:127]
	v_lshl_add_u64 v[126:127], v[198:199], 1, v[126:127]
	v_and_b32_e32 v115, 0x1fcf, v68
	v_cmp_le_u32_e64 s[4:5], 16, v115
	s_mov_b64 s[6:7], exec
	s_nop 0
	s_and_b64 exec, exec, s[4:5]
	global_load_dwordx4 v[112:115], v[126:127], off
	s_mov_b64 exec, s[6:7]
	s_waitcnt vmcnt(8)
	v_mov_b32_e32 v100, v81
	v_mov_b32_e32 v101, v82
	v_mov_b32_e32 v81, v83
	s_waitcnt vmcnt(7)
	v_mov_b32_e32 v82, v85
	v_mov_b32_e32 v83, v86
	v_mov_b32_e32 v85, v87
	v_pk_add_f32 v[80:81], v[100:101], v[80:81]
	v_pk_add_f32 v[82:83], v[82:83], v[84:85]
	v_mov_b32_e32 v85, v80
	v_mov_b32_e32 v84, v82
	v_mov_b32_e32 v80, v83
	v_pk_add_f32 v[80:81], v[84:85], v[80:81]
	s_waitcnt vmcnt(6)
	v_mov_b32_e32 v84, v93
	v_mov_b32_e32 v85, v94
	v_mov_b32_e32 v93, v95
	s_waitcnt vmcnt(5)
	v_mov_b32_e32 v86, v97
	v_mov_b32_e32 v87, v98
	v_mov_b32_e32 v97, v99
	v_pk_add_f32 v[84:85], v[84:85], v[92:93]
	v_pk_add_f32 v[86:87], v[86:87], v[96:97]
	v_mov_b32_e32 v93, v84
	v_mov_b32_e32 v92, v86
	v_mov_b32_e32 v84, v87
	v_pk_add_f32 v[92:93], v[92:93], v[84:85]
	ds_bpermute_b32 v83, v205, v81
	ds_bpermute_b32 v82, v205, v80
	ds_bpermute_b32 v95, v205, v93
	ds_bpermute_b32 v94, v205, v92
	s_waitcnt lgkmcnt(2)
	v_pk_add_f32 v[84:85], v[80:81], v[82:83]
	ds_bpermute_b32 v87, v242, v85
	s_waitcnt lgkmcnt(1)
	v_pk_add_f32 v[80:81], v[92:93], v[94:95]
	ds_bpermute_b32 v86, v242, v84
	ds_bpermute_b32 v83, v242, v81
	ds_bpermute_b32 v82, v242, v80
	s_and_saveexec_b64 s[4:5], vcc
	s_xor_b64 s[6:7], exec, s[4:5]
	s_cbranch_execz .LBB0_990
	v_mov_b32_e32 v115, 0
	v_mov_b32_e32 v114, 0
	v_mov_b32_e32 v113, 0
	v_mov_b32_e32 v112, 0
	s_and_saveexec_b64 s[82:83], s[0:1]
	s_cbranch_execz .LBB0_989
	v_readlane_b32 s4, v254, 11
	v_lshlrev_b32_e32 v69, 2, v117
	v_readlane_b32 s5, v254, 12
	s_nop 4
	global_load_dword v69, v69, s[4:5]
	v_readlane_b32 s4, v254, 19
	v_readlane_b32 s5, v254, 20
	s_waitcnt vmcnt(0)
	v_fmamk_f32 v69, v69, 0x3a800000, v241
	v_lshl_add_u64 v[92:93], s[4:5], 0, v[124:125]
	v_lshl_add_u64 v[96:97], v[198:199], 2, v[92:93]
	global_load_dwordx4 v[92:95], v[96:97], off
	s_nop 0
	global_load_dwordx4 v[96:99], v[96:97], off offset:16
	v_mul_f32_e32 v71, 0x4b800000, v69
	v_cmp_gt_f32_e64 s[4:5], s77, v69
	s_nop 1
	v_cndmask_b32_e64 v69, v69, v71, s[4:5]
	v_rsq_f32_e32 v69, v69
	s_nop 0
	v_mul_f32_e32 v71, 0x45800000, v69
	v_cndmask_b32_e64 v100, v69, v71, s[4:5]
	s_waitcnt vmcnt(1)
	v_pk_mul_f32 v[92:93], v[92:93], v[100:101] op_sel_hi:[1,0]
	v_pk_mul_f32 v[94:95], v[94:95], v[100:101] op_sel_hi:[1,0]
	s_waitcnt vmcnt(0)
	v_pk_mul_f32 v[96:97], v[96:97], v[100:101] op_sel_hi:[1,0]
	v_pk_mul_f32 v[98:99], v[100:101], v[98:99] op_sel_hi:[0,1]
	v_cvt_pk_bf16_f32 v112, v92, v93
	v_cvt_pk_bf16_f32 v113, v94, v95
	v_cvt_pk_bf16_f32 v114, v96, v97
	v_cvt_pk_bf16_f32 v115, v98, v99

.LBB0_990:
	s_or_saveexec_b64 s[4:5], s[6:7]
	v_add_u32_e32 v69, 0x70, v204
	v_cndmask_b32_e64 v69, v68, v69, s[0:1]
	v_mad_i64_i32 v[92:93], s[6:7], v69, s70, 0
	v_lshl_add_u64 v[92:93], s[12:13], 0, v[92:93]
	v_lshl_add_u64 v[126:127], v[198:199], 1, v[92:93]
	s_xor_b64 exec, exec, s[4:5]
	s_cbranch_execz .LBB0_992


.LBB0_1079:
	s_add_u32 s73, s38, 0x100
	v_mov_b32_e32 v0, 0
	s_addc_u32 s76, s39, 0
	s_mov_b32 s77, -2
	s_waitcnt lgkmcnt(0)
	v_mov_b32_e32 v1, 0
	v_mov_b64_e32 v[2:3], 0
	v_mov_b64_e32 v[4:5], 0
	v_mov_b64_e32 v[6:7], 0
	v_mov_b64_e32 v[8:9], 0
	v_mov_b64_e32 v[10:11], 0
	v_mov_b64_e32 v[12:13], 0
	v_mov_b64_e32 v[14:15], 0
	v_mov_b64_e32 v[16:17], 0
	v_mov_b64_e32 v[18:19], 0
	v_mov_b64_e32 v[20:21], 0
	v_mov_b64_e32 v[22:23], 0
	v_mov_b64_e32 v[24:25], 0
	v_mov_b64_e32 v[26:27], 0
	v_mov_b64_e32 v[28:29], 0
	v_mov_b64_e32 v[30:31], 0
	v_mov_b64_e32 v[32:33], 0
	v_mov_b64_e32 v[34:35], 0
	v_mov_b64_e32 v[36:37], 0
	v_mov_b64_e32 v[38:39], 0
	v_mov_b64_e32 v[40:41], 0
	v_mov_b64_e32 v[42:43], 0
	v_mov_b64_e32 v[44:45], 0
	v_mov_b64_e32 v[46:47], 0
	v_mov_b64_e32 v[48:49], 0
	v_mov_b64_e32 v[50:51], 0
	v_mov_b64_e32 v[52:53], 0
	v_mov_b64_e32 v[54:55], 0
	v_mov_b64_e32 v[56:57], 0
	v_mov_b64_e32 v[58:59], 0
	v_mov_b64_e32 v[60:61], 0
	v_mov_b64_e32 v[62:63], 0
	v_mov_b64_e32 v[64:65], 0
	v_mov_b64_e32 v[66:67], 0
	v_mov_b64_e32 v[68:69], 0
	v_mov_b64_e32 v[70:71], 0
	v_mov_b64_e32 v[72:73], 0
	v_mov_b64_e32 v[74:75], 0
	v_mov_b64_e32 v[76:77], 0
	v_mov_b64_e32 v[78:79], 0
	v_mov_b64_e32 v[80:81], 0
	v_mov_b64_e32 v[82:83], 0
	v_mov_b64_e32 v[84:85], 0
	v_mov_b64_e32 v[86:87], 0
	v_mov_b64_e32 v[88:89], 0
	v_mov_b64_e32 v[90:91], 0
	v_mov_b64_e32 v[92:93], 0
	v_mov_b64_e32 v[94:95], 0
	v_mov_b64_e32 v[96:97], 0
	v_mov_b64_e32 v[98:99], 0
	v_mov_b64_e32 v[100:101], 0
	v_mov_b64_e32 v[102:103], 0
	v_mov_b64_e32 v[104:105], 0
	v_mov_b64_e32 v[106:107], 0
	v_mov_b64_e32 v[108:109], 0
	v_mov_b64_e32 v[110:111], 0
	v_mov_b64_e32 v[112:113], 0
	v_mov_b64_e32 v[114:115], 0
	v_mov_b64_e32 v[116:117], 0
	v_mov_b64_e32 v[118:119], 0
	v_mov_b64_e32 v[120:121], 0
	v_mov_b64_e32 v[122:123], 0
	v_mov_b64_e32 v[124:125], 0
	v_mov_b64_e32 v[126:127], 0
	s_nop 0
	s_nop 0
	s_nop 0
	s_nop 0
	s_nop 0
	s_nop 0
	s_nop 0
	s_nop 0
	s_nop 0
	s_nop 0
	s_nop 0
	s_nop 0
	s_nop 0

.LBB0_1755:
	s_andn2_b64 vcc, exec, s[6:7]
	s_cbranch_vccnz .LBB0_1802
	v_add_u32_e32 v142, s4, v240
	v_ashrrev_i32_e32 v143, 31, v142
	v_add_u32_e32 v144, 16, v142
	v_lshlrev_b64 v[130:131], 6, v[142:143]
	v_ashrrev_i32_e32 v145, 31, v144
	v_add_u32_e32 v146, 32, v142
	v_lshl_add_u64 v[130:131], v[190:191], 0, v[130:131]
	v_lshlrev_b64 v[132:133], 6, v[144:145]
	v_ashrrev_i32_e32 v147, 31, v146
	v_lshl_add_u64 v[132:133], v[190:191], 0, v[132:133]
	global_load_dwordx4 v[150:153], v[130:131], off
	global_load_dwordx4 v[154:157], v[132:133], off
	v_lshlrev_b64 v[130:131], 6, v[146:147]
	v_add_u32_e32 v148, 48, v142
	v_lshl_add_u64 v[130:131], v[190:191], 0, v[130:131]
	v_ashrrev_i32_e32 v149, 31, v148
	global_load_dwordx4 v[158:161], v[130:131], off
	v_lshlrev_b64 v[130:131], 6, v[148:149]
	v_lshl_add_u64 v[130:131], v[190:191], 0, v[130:131]
	global_load_dwordx4 v[162:165], v[130:131], off
	v_add_u32_e32 v208, s2, v242
	v_ashrrev_i32_e32 v209, 31, v208
	v_lshl_add_u64 v[130:131], v[208:209], 1, s[24:25]
	v_mad_i64_i32 v[222:223], s[2:3], v142, s89, v[130:131]
	v_mad_i64_i32 v[224:225], s[2:3], v144, s89, v[130:131]
	v_mad_i64_i32 v[226:227], s[2:3], v146, s89, v[130:131]
	v_mad_i64_i32 v[228:229], s[2:3], v148, s89, v[130:131]
	global_load_dwordx4 v[174:177], v[222:223], off
	global_load_dwordx4 v[138:141], v[224:225], off
	global_load_dwordx4 v[134:137], v[226:227], off
	global_load_dwordx4 v[130:133], v[228:229], off
	v_and_b32_e32 v143, 64, v248
	v_xor_b32_e32 v1, 16, v248
	v_add_u32_e32 v143, 64, v143
	v_cmp_lt_i32_e32 vcc, v1, v143
	v_xor_b32_e32 v145, 32, v248
	v_add_u32_e32 v181, -16, v142
	v_cndmask_b32_e64 v181, v142, v181, s[0:1]
	v_mad_i64_i32 v[212:213], s[2:3], v181, s89, 0
	v_lshl_add_u64 v[212:213], s[24:25], 0, v[212:213]
	v_lshl_add_u64 v[212:213], v[208:209], 1, v[212:213]
	v_and_b32_e32 v181, 0x1fff, v142
	v_cmp_le_u32_e64 s[2:3], 16, v181
	s_mov_b64 s[4:5], exec
	s_nop 0
	s_and_b64 exec, exec, s[2:3]
	global_load_dwordx4 v[178:181], v[212:213], off
	s_mov_b64 exec, s[4:5]
	s_waitcnt vmcnt(0)
	v_mov_b32_e32 v166, v151
	v_mov_b32_e32 v167, v152
	v_mov_b32_e32 v151, v153
	v_mov_b32_e32 v152, v155
	v_mov_b32_e32 v153, v156
	v_mov_b32_e32 v155, v157
	v_mov_b32_e32 v156, v159
	v_mov_b32_e32 v157, v160
	v_mov_b32_e32 v159, v161
	v_mov_b32_e32 v160, v163
	v_mov_b32_e32 v161, v164
	v_mov_b32_e32 v163, v165
	v_pk_add_f32 v[150:151], v[166:167], v[150:151]
	v_pk_add_f32 v[152:153], v[152:153], v[154:155]
	v_pk_add_f32 v[156:157], v[156:157], v[158:159]
	v_pk_add_f32 v[158:159], v[160:161], v[162:163]
	v_cndmask_b32_e32 v1, v248, v1, vcc
	v_mov_b32_e32 v155, v150
	v_mov_b32_e32 v154, v152
	v_mov_b32_e32 v150, v153
	v_mov_b32_e32 v152, v158
	v_mov_b32_e32 v153, v156
	v_mov_b32_e32 v156, v159
	v_lshlrev_b32_e32 v1, 2, v1
	v_pk_add_f32 v[150:151], v[154:155], v[150:151]
	v_pk_add_f32 v[152:153], v[152:153], v[156:157]
	ds_bpermute_b32 v155, v1, v151
	ds_bpermute_b32 v154, v1, v150
	ds_bpermute_b32 v157, v1, v153
	ds_bpermute_b32 v156, v1, v152
	v_cmp_lt_i32_e32 vcc, v145, v143
	s_waitcnt lgkmcnt(0)
	v_pk_add_f32 v[154:155], v[150:151], v[154:155]
	v_cndmask_b32_e32 v1, v248, v145, vcc
	v_lshlrev_b32_e32 v1, 2, v1
	v_pk_add_f32 v[150:151], v[152:153], v[156:157]
	ds_bpermute_b32 v157, v1, v155
	ds_bpermute_b32 v156, v1, v154
	ds_bpermute_b32 v153, v1, v151
	ds_bpermute_b32 v152, v1, v150
	v_and_b32_e32 v1, 0x1fff, v142
	v_cmp_gt_u32_e32 vcc, 16, v1
	v_mul_hi_u32_u24_e32 v211, 0x2c00, v1
	v_mul_u32_u24_e32 v210, 0x2c00, v1
	s_and_saveexec_b64 s[2:3], vcc
	s_xor_b64 s[4:5], exec, s[2:3]
	s_cbranch_execz .LBB0_1760
	v_mov_b32_e32 v181, 0
	v_mov_b32_e32 v180, 0
	v_mov_b32_e32 v179, 0
	v_mov_b32_e32 v178, 0
	s_and_saveexec_b64 s[6:7], s[0:1]
	s_cbranch_execz .LBB0_1759
	v_readlane_b32 s2, v254, 11
	v_lshlrev_b32_e32 v143, 2, v1
	v_readlane_b32 s3, v254, 12
	s_nop 4
	global_load_dword v143, v143, s[2:3]
	v_readlane_b32 s2, v254, 19
	v_readlane_b32 s3, v254, 20
	s_waitcnt vmcnt(0)
	v_fmamk_f32 v143, v143, 0x3a800000, v247
	v_lshl_add_u64 v[158:159], s[2:3], 0, v[210:211]
	v_lshl_add_u64 v[162:163], v[208:209], 2, v[158:159]
	global_load_dwordx4 v[158:161], v[162:163], off
	s_nop 0
	global_load_dwordx4 v[162:165], v[162:163], off offset:16
	v_mul_f32_e32 v145, 0x4b800000, v143
	v_cmp_gt_f32_e64 s[2:3], s90, v143
	s_nop 1
	v_cndmask_b32_e64 v143, v143, v145, s[2:3]
	v_rsq_f32_e32 v143, v143
	s_nop 0
	v_mul_f32_e32 v145, 0x45800000, v143
	v_cndmask_b32_e64 v166, v143, v145, s[2:3]
	s_waitcnt vmcnt(1)
	v_pk_mul_f32 v[158:159], v[158:159], v[166:167] op_sel_hi:[1,0]
	v_pk_mul_f32 v[160:161], v[160:161], v[166:167] op_sel_hi:[1,0]
	s_waitcnt vmcnt(0)
	v_pk_mul_f32 v[162:163], v[162:163], v[166:167] op_sel_hi:[1,0]
	v_pk_mul_f32 v[164:165], v[166:167], v[164:165] op_sel_hi:[0,1]
	v_cvt_pk_bf16_f32 v178, v158, v159
	v_cvt_pk_bf16_f32 v179, v160, v161
	v_cvt_pk_bf16_f32 v180, v162, v163
	v_cvt_pk_bf16_f32 v181, v164, v165

.LBB0_1760:
	s_or_saveexec_b64 s[2:3], s[4:5]
	v_add_u32_e32 v143, -16, v142
	v_cndmask_b32_e64 v143, v142, v143, s[0:1]
	v_mad_i64_i32 v[158:159], s[4:5], v143, s89, 0
	v_lshl_add_u64 v[158:159], s[24:25], 0, v[158:159]
	v_lshl_add_u64 v[212:213], v[208:209], 1, v[158:159]
	s_xor_b64 exec, exec, s[2:3]
	s_cbranch_execz .LBB0_1762


.LBB0_1775:
	v_lshl_add_u32 v198, s97, 8, v240
	v_ashrrev_i32_e32 v199, 31, v198
	v_or_b32_e32 v150, 16, v198
	v_lshlrev_b64 v[130:131], 6, v[198:199]
	v_ashrrev_i32_e32 v151, 31, v150
	v_or_b32_e32 v152, 32, v198
	v_lshl_add_u64 v[130:131], v[190:191], 0, v[130:131]
	v_lshlrev_b64 v[132:133], 6, v[150:151]
	v_ashrrev_i32_e32 v153, 31, v152
	v_lshl_add_u64 v[132:133], v[190:191], 0, v[132:133]
	global_load_dwordx4 v[142:145], v[130:131], off
	global_load_dwordx4 v[146:149], v[132:133], off
	v_lshlrev_b64 v[130:131], 6, v[152:153]
	v_or_b32_e32 v154, 48, v198
	v_lshl_add_u64 v[130:131], v[190:191], 0, v[130:131]
	v_ashrrev_i32_e32 v155, 31, v154
	global_load_dwordx4 v[156:159], v[130:131], off
	v_lshlrev_b64 v[130:131], 6, v[154:155]
	v_lshl_add_u64 v[130:131], v[190:191], 0, v[130:131]
	global_load_dwordx4 v[160:163], v[130:131], off
	v_lshl_or_b32 v202, s95, 8, v242
	v_ashrrev_i32_e32 v203, 31, v202
	v_lshl_add_u64 v[200:201], v[202:203], 1, s[24:25]
	v_mad_i64_i32 v[130:131], s[2:3], v198, s89, v[200:201]
	v_mad_i64_i32 v[132:133], s[2:3], v150, s89, v[200:201]
	v_mad_i64_i32 v[134:135], s[2:3], v152, s89, v[200:201]
	v_mad_i64_i32 v[164:165], s[2:3], v154, s89, v[200:201]
	global_load_dwordx4 v[174:177], v[130:131], off
	global_load_dwordx4 v[138:141], v[132:133], off
	s_nop 0
	global_load_dwordx4 v[134:137], v[134:135], off
	s_nop 0
	global_load_dwordx4 v[130:133], v[164:165], off
	v_and_b32_e32 v151, 64, v248
	v_xor_b32_e32 v1, 16, v248
	v_add_u32_e32 v151, 64, v151
	v_cmp_lt_i32_e32 vcc, v1, v151
	v_xor_b32_e32 v153, 32, v248
	v_and_b32_e32 v215, 0x1fcf, v198
	v_cndmask_b32_e32 v1, v248, v1, vcc
	v_lshlrev_b32_e32 v1, 2, v1
	v_cmp_lt_i32_e32 vcc, v153, v151
	v_mul_hi_u32_u24_e32 v223, 0x2c00, v215
	v_mul_u32_u24_e32 v222, 0x2c00, v215
	v_cndmask_b32_e32 v151, v248, v153, vcc
	v_lshlrev_b32_e32 v199, 2, v151
	v_cmp_gt_u32_e32 vcc, 16, v215
	v_add_u32_e32 v181, -16, v198
	v_cndmask_b32_e64 v181, v198, v181, s[0:1]
	v_mad_i64_i32 v[224:225], s[2:3], v181, s89, 0
	v_lshl_add_u64 v[224:225], s[24:25], 0, v[224:225]
	v_lshl_add_u64 v[224:225], v[202:203], 1, v[224:225]
	v_and_b32_e32 v181, 0x1fcf, v198
	v_cmp_le_u32_e64 s[2:3], 16, v181
	s_mov_b64 s[4:5], exec
	s_nop 0
	s_and_b64 exec, exec, s[2:3]
	global_load_dwordx4 v[178:181], v[224:225], off
	s_mov_b64 exec, s[4:5]
	s_waitcnt vmcnt(0)
	v_mov_b32_e32 v164, v143
	v_mov_b32_e32 v165, v144
	v_mov_b32_e32 v143, v145
	v_mov_b32_e32 v144, v147
	v_mov_b32_e32 v145, v148
	v_mov_b32_e32 v147, v149
	v_mov_b32_e32 v148, v157
	v_mov_b32_e32 v149, v158
	v_mov_b32_e32 v157, v159
	v_mov_b32_e32 v158, v161
	v_mov_b32_e32 v159, v162
	v_mov_b32_e32 v161, v163
	v_pk_add_f32 v[142:143], v[164:165], v[142:143]
	v_pk_add_f32 v[144:145], v[144:145], v[146:147]
	v_pk_add_f32 v[148:149], v[148:149], v[156:157]
	v_pk_add_f32 v[156:157], v[158:159], v[160:161]
	v_mov_b32_e32 v147, v142
	v_mov_b32_e32 v146, v144
	v_mov_b32_e32 v142, v145
	v_mov_b32_e32 v144, v156
	v_mov_b32_e32 v145, v148
	v_mov_b32_e32 v148, v157
	v_pk_add_f32 v[142:143], v[146:147], v[142:143]
	v_pk_add_f32 v[144:145], v[144:145], v[148:149]
	ds_bpermute_b32 v147, v1, v143
	ds_bpermute_b32 v146, v1, v142
	ds_bpermute_b32 v149, v1, v145
	ds_bpermute_b32 v148, v1, v144
	s_waitcnt lgkmcnt(0)
	v_pk_add_f32 v[162:163], v[142:143], v[146:147]
	ds_bpermute_b32 v171, v199, v163
	v_pk_add_f32 v[156:157], v[144:145], v[148:149]
	ds_bpermute_b32 v170, v199, v162
	ds_bpermute_b32 v165, v199, v157
	ds_bpermute_b32 v164, v199, v156
	s_and_saveexec_b64 s[2:3], vcc
	s_xor_b64 s[4:5], exec, s[2:3]
	s_cbranch_execz .LBB0_1779
	v_mov_b32_e32 v181, 0
	v_mov_b32_e32 v180, 0
	v_mov_b32_e32 v179, 0
	v_mov_b32_e32 v178, 0
	s_and_saveexec_b64 s[6:7], s[0:1]
	s_cbranch_execz .LBB0_1778
	v_readlane_b32 s2, v254, 11
	v_lshlrev_b32_e32 v142, 2, v215
	v_readlane_b32 s3, v254, 12
	s_nop 4
	global_load_dword v151, v142, s[2:3]
	v_readlane_b32 s2, v254, 19
	v_readlane_b32 s3, v254, 20
	s_waitcnt vmcnt(0)
	v_fmamk_f32 v151, v151, 0x3a800000, v247
	v_lshl_add_u64 v[142:143], s[2:3], 0, v[222:223]
	v_lshl_add_u64 v[146:147], v[202:203], 2, v[142:143]
	global_load_dwordx4 v[142:145], v[146:147], off
	s_nop 0
	global_load_dwordx4 v[146:149], v[146:147], off offset:16
	v_mul_f32_e32 v153, 0x4b800000, v151
	v_cmp_gt_f32_e64 s[2:3], s90, v151
	s_nop 1
	v_cndmask_b32_e64 v151, v151, v153, s[2:3]
	v_rsq_f32_e32 v151, v151
	s_nop 0
	v_mul_f32_e32 v153, 0x45800000, v151
	v_cndmask_b32_e64 v158, v151, v153, s[2:3]
	s_waitcnt vmcnt(1)
	v_pk_mul_f32 v[142:143], v[142:143], v[158:159] op_sel_hi:[1,0]
	v_pk_mul_f32 v[144:145], v[144:145], v[158:159] op_sel_hi:[1,0]
	s_waitcnt vmcnt(0)
	v_pk_mul_f32 v[146:147], v[146:147], v[158:159] op_sel_hi:[1,0]
	v_pk_mul_f32 v[148:149], v[158:159], v[148:149] op_sel_hi:[0,1]
	v_cvt_pk_bf16_f32 v178, v142, v143
	v_cvt_pk_bf16_f32 v179, v144, v145
	v_cvt_pk_bf16_f32 v180, v146, v147
	v_cvt_pk_bf16_f32 v181, v148, v149

.LBB0_1779:
	s_or_saveexec_b64 s[2:3], s[4:5]
	v_add_u32_e32 v142, -16, v198
	v_cndmask_b32_e64 v142, v198, v142, s[0:1]
	v_mad_i64_i32 v[142:143], s[4:5], v142, s89, 0
	v_lshl_add_u64 v[142:143], s[24:25], 0, v[142:143]
	v_lshl_add_u64 v[224:225], v[202:203], 1, v[142:143]
	s_xor_b64 exec, exec, s[2:3]
	s_cbranch_execz .LBB0_1781


.LBB0_1787:
	s_or_b64 exec, exec, s[2:3]
	v_lshlrev_b64 v[118:119], 2, v[208:209]
	v_lshl_add_u64 v[154:155], s[18:19], 0, v[118:119]
	v_lshl_add_u64 v[156:157], s[22:23], 0, v[118:119]
	global_load_dwordx4 v[106:109], v[154:155], off offset:16
	global_load_dwordx4 v[122:125], v[154:155], off
	global_load_dwordx4 v[134:137], v[156:157], off
	global_load_dwordx4 v[110:113], v[156:157], off offset:16
	v_lshl_add_u64 v[166:167], s[42:43], 0, v[118:119]
	global_load_dwordx4 v[130:133], v[166:167], off
	global_load_dwordx4 v[114:117], v[166:167], off offset:16
	v_lshl_add_u64 v[168:169], s[20:21], 0, v[118:119]
	global_load_dwordx4 v[126:129], v[168:169], off
	global_load_dwordx4 v[118:121], v[168:169], off offset:16
	s_nop 0
	s_nop 0
	s_nop 0
	s_nop 0
	s_nop 0
	s_waitcnt vmcnt(8)
	v_mov_b32_dpp v164, v146 row_ror:1 row_mask:0xf bank_mask:0xf
	v_mov_b32_dpp v165, v146 row_ror:2 row_mask:0xf bank_mask:0xf
	v_mov_b32_dpp v171, v147 row_ror:1 row_mask:0xf bank_mask:0xf
	v_mov_b32_dpp v172, v147 row_ror:2 row_mask:0xf bank_mask:0xf
	s_nop 0
	s_nop 0
	s_nop 0
	v_mov_b32_dpp v223, v148 row_ror:2 row_mask:0xf bank_mask:0xf
	v_mov_b32_dpp v164, v142 row_shr:1 row_mask:0xf bank_mask:0xf
	v_mov_b32_dpp v165, v142 row_shr:2 row_mask:0xf bank_mask:0xf
	v_mov_b32_dpp v171, v143 row_shr:1 row_mask:0xf bank_mask:0xf
	v_mov_b32_dpp v172, v143 row_shr:2 row_mask:0xf bank_mask:0xf
	v_mov_b32_dpp v173, v148 row_ror:1 row_mask:0xf bank_mask:0xf
	v_mov_b32_dpp v224, v149 row_ror:1 row_mask:0xf bank_mask:0xf
	v_mov_b32_dpp v225, v149 row_ror:2 row_mask:0xf bank_mask:0xf
	v_mov_b32_dpp v223, v144 row_shr:2 row_mask:0xf bank_mask:0xf
	v_lshlrev_b32_e32 v146, 16, v164
	v_lshlrev_b32_e32 v148, 16, v165
	v_and_b32_e32 v147, 0xffff0000, v164
	v_and_b32_e32 v149, 0xffff0000, v165
	v_lshlrev_b32_e32 v164, 16, v171
	v_lshlrev_b32_e32 v170, 16, v172
	v_and_b32_e32 v165, 0xffff0000, v171
	v_and_b32_e32 v171, 0xffff0000, v172
	v_mov_b32_dpp v173, v144 row_shr:1 row_mask:0xf bank_mask:0xf
	v_lshlrev_b32_e32 v222, 16, v223
	v_and_b32_e32 v223, 0xffff0000, v223
	v_lshlrev_b32_e32 v158, 16, v142
	v_and_b32_e32 v159, 0xffff0000, v142
	v_lshlrev_b32_e32 v160, 16, v143
	v_and_b32_e32 v161, 0xffff0000, v143
	v_lshlrev_b32_e32 v172, 16, v173
	v_and_b32_e32 v173, 0xffff0000, v173
	v_lshlrev_b32_e32 v162, 16, v144
	v_and_b32_e32 v163, 0xffff0000, v144
	v_mov_b32_e32 v221, v220
	v_pk_mul_f32 v[94:95], v[94:95], v[220:221]
	v_pk_mul_f32 v[96:97], v[96:97], v[220:221]
	v_mov_b32_dpp v225, v145 row_shr:2 row_mask:0xf bank_mask:0xf
	v_mov_b32_dpp v224, v145 row_shr:1 row_mask:0xf bank_mask:0xf
	v_pk_mul_f32 v[92:93], v[92:93], v[220:221]
	v_pk_mul_f32 v[90:91], v[90:91], v[220:221]
	v_mov_b32_e32 v219, v218
	v_pk_mul_f32 v[86:87], v[86:87], v[218:219]
	v_pk_mul_f32 v[88:89], v[88:89], v[218:219]
	v_pk_mul_f32 v[82:83], v[82:83], v[218:219]
	v_pk_mul_f32 v[84:85], v[84:85], v[218:219]
	v_mov_b32_e32 v217, v216
	v_pk_mul_f32 v[78:79], v[78:79], v[216:217]
	v_pk_mul_f32 v[80:81], v[80:81], v[216:217]
	v_pk_mul_f32 v[74:75], v[74:75], v[216:217]
	v_pk_mul_f32 v[76:77], v[76:77], v[216:217]
	v_mov_b32_e32 v215, v214
	v_pk_mul_f32 v[70:71], v[70:71], v[214:215]
	v_pk_mul_f32 v[72:73], v[72:73], v[214:215]
	v_pk_mul_f32 v[66:67], v[66:67], v[214:215]
	v_pk_mul_f32 v[68:69], v[68:69], v[214:215]
	s_waitcnt vmcnt(5)
	v_pk_fma_f32 v[148:149], v[122:123], v[148:149], v[134:135]
	v_pk_fma_f32 v[170:171], v[124:125], v[170:171], v[136:137]
	s_waitcnt vmcnt(4)
	v_pk_fma_f32 v[222:223], v[106:107], v[222:223], v[110:111]
	s_waitcnt vmcnt(3)
	v_pk_fma_f32 v[146:147], v[130:131], v[146:147], v[148:149]
	v_pk_fma_f32 v[148:149], v[132:133], v[164:165], v[170:171]
	s_waitcnt vmcnt(2)
	v_pk_fma_f32 v[164:165], v[114:115], v[172:173], v[222:223]
	s_waitcnt vmcnt(1)
	v_pk_fma_f32 v[146:147], v[126:127], v[158:159], v[146:147]
	v_pk_fma_f32 v[148:149], v[128:129], v[160:161], v[148:149]
	s_waitcnt vmcnt(0)
	v_pk_fma_f32 v[158:159], v[118:119], v[162:163], v[164:165]
	v_mul_f32_e32 v160, 0xbfb8aa3b, v146
	v_mul_f32_e32 v161, 0xbfb8aa3b, v147
	v_mul_f32_e32 v162, 0xbfb8aa3b, v148
	v_mul_f32_e32 v163, 0xbfb8aa3b, v149
	v_exp_f32_e32 v160, v160
	v_exp_f32_e32 v161, v161
	v_exp_f32_e32 v162, v162
	v_exp_f32_e32 v163, v163
	v_add_f32_e32 v160, 1.0, v160
	v_add_f32_e32 v161, 1.0, v161
	v_add_f32_e32 v162, 1.0, v162
	v_add_f32_e32 v163, 1.0, v163
	v_rcp_f32_e32 v160, v160
	v_rcp_f32_e32 v161, v161
	v_rcp_f32_e32 v162, v162
	v_rcp_f32_e32 v163, v163
	v_mul_f32_e32 v164, 0xbfb8aa3b, v158
	v_pk_mul_f32 v[146:147], v[146:147], v[160:161]
	v_mul_f32_e32 v165, 0xbfb8aa3b, v159
	v_pk_mul_f32 v[148:149], v[148:149], v[162:163]
	v_pk_mul_f32 v[94:95], v[94:95], v[146:147]
	v_pk_mul_f32 v[96:97], v[96:97], v[148:149]
	v_lshlrev_b32_e32 v146, 16, v225
	v_and_b32_e32 v147, 0xffff0000, v225
	v_cvt_pk_bf16_f32 v94, v94, v95
	v_cvt_pk_bf16_f32 v95, v96, v97
	v_lshlrev_b32_e32 v96, 16, v224
	v_and_b32_e32 v97, 0xffff0000, v224
	v_pk_fma_f32 v[146:147], v[108:109], v[146:147], v[112:113]
	v_lshlrev_b32_e32 v148, 16, v145
	v_and_b32_e32 v149, 0xffff0000, v145
	v_pk_fma_f32 v[96:97], v[116:117], v[96:97], v[146:147]
	v_exp_f32_e32 v164, v164
	v_pk_fma_f32 v[96:97], v[120:121], v[148:149], v[96:97]
	v_exp_f32_e32 v165, v165
	v_mul_f32_e32 v146, 0xbfb8aa3b, v96
	v_mul_f32_e32 v147, 0xbfb8aa3b, v97
	v_exp_f32_e32 v146, v146
	v_exp_f32_e32 v147, v147
	v_add_f32_e32 v164, 1.0, v164
	v_add_f32_e32 v160, 1.0, v165
	v_add_f32_e32 v146, 1.0, v146
	v_add_f32_e32 v147, 1.0, v147
	v_rcp_f32_e32 v146, v146
	v_rcp_f32_e32 v147, v147
	v_rcp_f32_e32 v164, v164
	v_rcp_f32_e32 v165, v160
	v_pk_mul_f32 v[96:97], v[96:97], v[146:147]
	s_nop 0
	v_pk_mul_f32 v[92:93], v[92:93], v[96:97]
	v_pk_mul_f32 v[148:149], v[158:159], v[164:165]
	v_cvt_pk_bf16_f32 v97, v92, v93
	v_pk_mul_f32 v[90:91], v[90:91], v[148:149]
	s_nop 0
	v_cvt_pk_bf16_f32 v96, v90, v91
	s_nop 0
	v_mov_b32_dpp v93, v142 row_ror:2 row_mask:0xf bank_mask:0xf
	global_store_dwordx4 v[180:181], v[94:97], off offset:256
	v_mov_b32_dpp v91, v142 row_ror:1 row_mask:0xf bank_mask:0xf
	v_mov_b32_dpp v93, v138 row_shr:2 row_mask:0xf bank_mask:0xf
	s_nop 0
	v_mov_b32_dpp v91, v138 row_shr:1 row_mask:0xf bank_mask:0xf
	s_nop 0
	v_lshlrev_b32_e32 v92, 16, v93
	v_and_b32_e32 v93, 0xffff0000, v93
	v_mov_b32_dpp v97, v143 row_ror:1 row_mask:0xf bank_mask:0xf
	v_mov_b32_dpp v142, v143 row_ror:2 row_mask:0xf bank_mask:0xf
	v_lshlrev_b32_e32 v90, 16, v91
	v_and_b32_e32 v91, 0xffff0000, v91
	v_pk_fma_f32 v[92:93], v[122:123], v[92:93], v[134:135]
	v_mov_b32_dpp v97, v139 row_shr:1 row_mask:0xf bank_mask:0xf
	v_lshlrev_b32_e32 v94, 16, v138
	v_and_b32_e32 v95, 0xffff0000, v138
	v_pk_fma_f32 v[90:91], v[130:131], v[90:91], v[92:93]
	v_mov_b32_dpp v142, v139 row_shr:2 row_mask:0xf bank_mask:0xf
	v_pk_fma_f32 v[90:91], v[126:127], v[94:95], v[90:91]
	v_lshlrev_b32_e32 v94, 16, v97
	v_lshlrev_b32_e32 v96, 16, v142
	v_and_b32_e32 v95, 0xffff0000, v97
	v_and_b32_e32 v97, 0xffff0000, v142
	v_pk_fma_f32 v[96:97], v[124:125], v[96:97], v[136:137]
	v_lshlrev_b32_e32 v142, 16, v139
	v_and_b32_e32 v143, 0xffff0000, v139
	v_pk_fma_f32 v[94:95], v[132:133], v[94:95], v[96:97]
	v_mul_f32_e32 v92, 0xbfb8aa3b, v90
	v_mul_f32_e32 v93, 0xbfb8aa3b, v91
	v_pk_fma_f32 v[94:95], v[128:129], v[142:143], v[94:95]
	v_exp_f32_e32 v92, v92
	v_exp_f32_e32 v93, v93
	v_mul_f32_e32 v96, 0xbfb8aa3b, v94
	v_mul_f32_e32 v97, 0xbfb8aa3b, v95
	v_exp_f32_e32 v96, v96
	v_exp_f32_e32 v97, v97
	v_add_f32_e32 v92, 1.0, v92
	v_add_f32_e32 v93, 1.0, v93
	v_rcp_f32_e32 v92, v92
	v_rcp_f32_e32 v93, v93
	v_add_f32_e32 v96, 1.0, v96
	v_add_f32_e32 v97, 1.0, v97
	v_rcp_f32_e32 v96, v96
	v_rcp_f32_e32 v97, v97
	v_pk_mul_f32 v[90:91], v[90:91], v[92:93]
	v_lshlrev_b32_e32 v92, 16, v140
	v_pk_mul_f32 v[86:87], v[86:87], v[90:91]
	v_pk_mul_f32 v[90:91], v[94:95], v[96:97]
	v_cvt_pk_bf16_f32 v86, v86, v87
	v_pk_mul_f32 v[88:89], v[88:89], v[90:91]
	s_nop 0
	v_cvt_pk_bf16_f32 v87, v88, v89
	s_nop 0
	v_mov_b32_dpp v91, v144 row_ror:2 row_mask:0xf bank_mask:0xf
	s_nop 0
	v_mov_b32_dpp v89, v144 row_ror:1 row_mask:0xf bank_mask:0xf
	v_mov_b32_dpp v91, v140 row_shr:2 row_mask:0xf bank_mask:0xf
	s_nop 0
	v_mov_b32_dpp v89, v140 row_shr:1 row_mask:0xf bank_mask:0xf
	v_lshlrev_b32_e32 v90, 16, v91
	v_and_b32_e32 v91, 0xffff0000, v91
	v_mov_b32_dpp v95, v145 row_ror:1 row_mask:0xf bank_mask:0xf
	v_mov_b32_dpp v96, v145 row_ror:2 row_mask:0xf bank_mask:0xf
	v_lshlrev_b32_e32 v88, 16, v89
	v_and_b32_e32 v89, 0xffff0000, v89
	v_pk_fma_f32 v[90:91], v[106:107], v[90:91], v[110:111]
	v_mov_b32_dpp v95, v141 row_shr:1 row_mask:0xf bank_mask:0xf
	v_and_b32_e32 v93, 0xffff0000, v140
	v_pk_fma_f32 v[88:89], v[114:115], v[88:89], v[90:91]
	v_mov_b32_dpp v96, v141 row_shr:2 row_mask:0xf bank_mask:0xf
	v_pk_fma_f32 v[88:89], v[118:119], v[92:93], v[88:89]
	v_lshlrev_b32_e32 v92, 16, v95
	v_lshlrev_b32_e32 v94, 16, v96
	v_and_b32_e32 v93, 0xffff0000, v95
	v_and_b32_e32 v95, 0xffff0000, v96
	v_pk_fma_f32 v[94:95], v[108:109], v[94:95], v[112:113]
	v_lshlrev_b32_e32 v96, 16, v141
	v_and_b32_e32 v97, 0xffff0000, v141
	v_pk_fma_f32 v[92:93], v[116:117], v[92:93], v[94:95]
	v_mul_f32_e32 v90, 0xbfb8aa3b, v88
	v_mul_f32_e32 v91, 0xbfb8aa3b, v89
	v_pk_fma_f32 v[92:93], v[120:121], v[96:97], v[92:93]
	v_exp_f32_e32 v90, v90
	v_exp_f32_e32 v91, v91
	v_mul_f32_e32 v94, 0xbfb8aa3b, v92
	v_mul_f32_e32 v95, 0xbfb8aa3b, v93
	v_exp_f32_e32 v94, v94
	v_exp_f32_e32 v95, v95
	v_add_f32_e32 v90, 1.0, v90
	v_add_f32_e32 v91, 1.0, v91
	v_rcp_f32_e32 v90, v90
	v_rcp_f32_e32 v91, v91
	v_add_f32_e32 v94, 1.0, v94
	v_add_f32_e32 v95, 1.0, v95
	v_rcp_f32_e32 v94, v94
	v_rcp_f32_e32 v95, v95
	v_pk_mul_f32 v[88:89], v[88:89], v[90:91]
	s_nop 0
	v_pk_mul_f32 v[82:83], v[82:83], v[88:89]
	v_pk_mul_f32 v[88:89], v[92:93], v[94:95]
	v_mov_b32_dpp v90, v139 row_ror:2 row_mask:0xf bank_mask:0xf
	v_pk_mul_f32 v[84:85], v[84:85], v[88:89]
	v_cvt_pk_bf16_f32 v88, v82, v83
	v_cvt_pk_bf16_f32 v89, v84, v85
	s_nop 0
	s_nop 0
	global_store_dwordx4 v[174:175], v[86:89], off offset:256
	v_mov_b32_dpp v85, v138 row_ror:2 row_mask:0xf bank_mask:0xf
	v_mov_b32_dpp v83, v138 row_ror:1 row_mask:0xf bank_mask:0xf
	s_nop 0
	v_mov_b32_dpp v85, v102 row_shr:2 row_mask:0xf bank_mask:0xf
	v_mov_b32_dpp v83, v102 row_shr:1 row_mask:0xf bank_mask:0xf
	v_lshlrev_b32_e32 v84, 16, v85
	v_and_b32_e32 v85, 0xffff0000, v85
	v_mov_b32_dpp v89, v139 row_ror:1 row_mask:0xf bank_mask:0xf
	v_lshlrev_b32_e32 v82, 16, v83
	v_and_b32_e32 v83, 0xffff0000, v83
	v_pk_fma_f32 v[84:85], v[122:123], v[84:85], v[134:135]
	v_mov_b32_dpp v89, v103 row_shr:1 row_mask:0xf bank_mask:0xf
	v_lshlrev_b32_e32 v86, 16, v102
	v_and_b32_e32 v87, 0xffff0000, v102
	v_pk_fma_f32 v[82:83], v[130:131], v[82:83], v[84:85]
	v_mov_b32_dpp v90, v103 row_shr:2 row_mask:0xf bank_mask:0xf
	v_pk_fma_f32 v[82:83], v[126:127], v[86:87], v[82:83]
	v_lshlrev_b32_e32 v86, 16, v89
	v_lshlrev_b32_e32 v88, 16, v90
	v_and_b32_e32 v87, 0xffff0000, v89
	v_and_b32_e32 v89, 0xffff0000, v90
	v_pk_fma_f32 v[88:89], v[124:125], v[88:89], v[136:137]
	v_lshlrev_b32_e32 v90, 16, v103
	v_and_b32_e32 v91, 0xffff0000, v103
	v_pk_fma_f32 v[86:87], v[132:133], v[86:87], v[88:89]
	v_mul_f32_e32 v84, 0xbfb8aa3b, v82
	v_mul_f32_e32 v85, 0xbfb8aa3b, v83
	v_pk_fma_f32 v[86:87], v[128:129], v[90:91], v[86:87]
	v_exp_f32_e32 v84, v84
	v_exp_f32_e32 v85, v85
	v_mul_f32_e32 v88, 0xbfb8aa3b, v86
	v_mul_f32_e32 v89, 0xbfb8aa3b, v87
	v_exp_f32_e32 v88, v88
	v_exp_f32_e32 v89, v89
	v_add_f32_e32 v84, 1.0, v84
	v_add_f32_e32 v85, 1.0, v85
	v_rcp_f32_e32 v84, v84
	v_rcp_f32_e32 v85, v85
	v_add_f32_e32 v88, 1.0, v88
	v_add_f32_e32 v89, 1.0, v89
	v_rcp_f32_e32 v88, v88
	v_rcp_f32_e32 v89, v89
	v_pk_mul_f32 v[82:83], v[82:83], v[84:85]
	v_lshlrev_b32_e32 v84, 16, v104
	v_pk_mul_f32 v[78:79], v[78:79], v[82:83]
	v_pk_mul_f32 v[82:83], v[86:87], v[88:89]
	v_cvt_pk_bf16_f32 v78, v78, v79
	v_pk_mul_f32 v[80:81], v[80:81], v[82:83]
	s_nop 0
	v_cvt_pk_bf16_f32 v79, v80, v81
	s_nop 0
	v_mov_b32_dpp v83, v140 row_ror:2 row_mask:0xf bank_mask:0xf
	s_nop 0
	v_mov_b32_dpp v81, v140 row_ror:1 row_mask:0xf bank_mask:0xf
	v_mov_b32_dpp v83, v104 row_shr:2 row_mask:0xf bank_mask:0xf
	s_nop 0
	v_mov_b32_dpp v81, v104 row_shr:1 row_mask:0xf bank_mask:0xf
	v_lshlrev_b32_e32 v82, 16, v83
	v_and_b32_e32 v83, 0xffff0000, v83
	v_mov_b32_dpp v87, v141 row_ror:1 row_mask:0xf bank_mask:0xf
	v_mov_b32_dpp v88, v141 row_ror:2 row_mask:0xf bank_mask:0xf
	v_lshlrev_b32_e32 v80, 16, v81
	v_and_b32_e32 v81, 0xffff0000, v81
	v_pk_fma_f32 v[82:83], v[106:107], v[82:83], v[110:111]
	v_mov_b32_dpp v87, v105 row_shr:1 row_mask:0xf bank_mask:0xf
	v_and_b32_e32 v85, 0xffff0000, v104
	v_pk_fma_f32 v[80:81], v[114:115], v[80:81], v[82:83]
	v_mov_b32_dpp v88, v105 row_shr:2 row_mask:0xf bank_mask:0xf
	v_pk_fma_f32 v[80:81], v[118:119], v[84:85], v[80:81]
	v_lshlrev_b32_e32 v84, 16, v87
	v_lshlrev_b32_e32 v86, 16, v88
	v_and_b32_e32 v85, 0xffff0000, v87
	v_and_b32_e32 v87, 0xffff0000, v88
	v_pk_fma_f32 v[86:87], v[108:109], v[86:87], v[112:113]
	v_lshlrev_b32_e32 v88, 16, v105
	v_and_b32_e32 v89, 0xffff0000, v105
	v_pk_fma_f32 v[84:85], v[116:117], v[84:85], v[86:87]
	v_mul_f32_e32 v82, 0xbfb8aa3b, v80
	v_mul_f32_e32 v83, 0xbfb8aa3b, v81
	v_pk_fma_f32 v[84:85], v[120:121], v[88:89], v[84:85]
	v_exp_f32_e32 v82, v82
	v_exp_f32_e32 v83, v83
	v_mul_f32_e32 v86, 0xbfb8aa3b, v84
	v_mul_f32_e32 v87, 0xbfb8aa3b, v85
	v_exp_f32_e32 v86, v86
	v_exp_f32_e32 v87, v87
	v_add_f32_e32 v82, 1.0, v82
	v_add_f32_e32 v83, 1.0, v83
	v_rcp_f32_e32 v82, v82
	v_rcp_f32_e32 v83, v83
	v_add_f32_e32 v86, 1.0, v86
	v_add_f32_e32 v87, 1.0, v87
	v_rcp_f32_e32 v86, v86
	v_rcp_f32_e32 v87, v87
	v_pk_mul_f32 v[80:81], v[80:81], v[82:83]
	s_nop 0
	v_pk_mul_f32 v[74:75], v[74:75], v[80:81]
	v_pk_mul_f32 v[80:81], v[84:85], v[86:87]
	s_nop 0
	v_pk_mul_f32 v[76:77], v[76:77], v[80:81]
	v_cvt_pk_bf16_f32 v80, v74, v75
	s_nop 0
	v_cvt_pk_bf16_f32 v81, v76, v77
	s_nop 0
	v_mov_b32_dpp v75, v102 row_ror:2 row_mask:0xf bank_mask:0xf
	global_store_dwordx4 v[176:177], v[78:81], off offset:256
	v_mov_b32_dpp v77, v102 row_ror:1 row_mask:0xf bank_mask:0xf
	v_mov_b32_dpp v75, v98 row_shr:2 row_mask:0xf bank_mask:0xf
	v_lshlrev_b32_e32 v74, 16, v75
	v_mov_b32_dpp v77, v98 row_shr:1 row_mask:0xf bank_mask:0xf
	v_and_b32_e32 v75, 0xffff0000, v75
	v_lshlrev_b32_e32 v76, 16, v77
	v_and_b32_e32 v77, 0xffff0000, v77
	v_pk_fma_f32 v[74:75], v[122:123], v[74:75], v[134:135]
	s_nop 0
	v_pk_fma_f32 v[74:75], v[130:131], v[76:77], v[74:75]
	v_lshlrev_b32_e32 v76, 16, v98
	v_and_b32_e32 v77, 0xffff0000, v98
	v_pk_fma_f32 v[74:75], v[126:127], v[76:77], v[74:75]
	s_nop 0
	v_mul_f32_e32 v76, 0xbfb8aa3b, v74
	v_mul_f32_e32 v77, 0xbfb8aa3b, v75
	v_exp_f32_e32 v76, v76
	v_exp_f32_e32 v77, v77
	v_mov_b32_dpp v80, v103 row_ror:2 row_mask:0xf bank_mask:0xf
	v_mov_b32_dpp v78, v103 row_ror:1 row_mask:0xf bank_mask:0xf
	v_add_f32_e32 v76, 1.0, v76
	v_add_f32_e32 v77, 1.0, v77
	v_rcp_f32_e32 v76, v76
	v_rcp_f32_e32 v77, v77
	v_mov_b32_dpp v80, v99 row_shr:2 row_mask:0xf bank_mask:0xf
	v_mov_b32_dpp v78, v99 row_shr:1 row_mask:0xf bank_mask:0xf
	v_lshlrev_b32_e32 v82, 16, v78
	v_pk_mul_f32 v[74:75], v[74:75], v[76:77]
	v_lshlrev_b32_e32 v76, 16, v80
	v_and_b32_e32 v77, 0xffff0000, v80
	v_and_b32_e32 v83, 0xffff0000, v78
	v_pk_fma_f32 v[76:77], v[124:125], v[76:77], v[136:137]
	s_nop 0
	v_pk_fma_f32 v[76:77], v[132:133], v[82:83], v[76:77]
	v_lshlrev_b32_e32 v82, 16, v99
	v_and_b32_e32 v83, 0xffff0000, v99
	v_mov_b32_dpp v86, v104 row_ror:2 row_mask:0xf bank_mask:0xf
	v_pk_fma_f32 v[76:77], v[128:129], v[82:83], v[76:77]
	v_mov_b32_dpp v85, v104 row_ror:1 row_mask:0xf bank_mask:0xf
	v_mov_b32_dpp v86, v100 row_shr:2 row_mask:0xf bank_mask:0xf
	v_mul_f32_e32 v78, 0xbfb8aa3b, v76
	v_mov_b32_dpp v85, v100 row_shr:1 row_mask:0xf bank_mask:0xf
	v_exp_f32_e32 v78, v78
	v_lshlrev_b32_e32 v82, 16, v86
	v_and_b32_e32 v83, 0xffff0000, v86
	v_lshlrev_b32_e32 v84, 16, v85
	v_and_b32_e32 v85, 0xffff0000, v85
	v_pk_fma_f32 v[82:83], v[106:107], v[82:83], v[110:111]
	v_pk_mul_f32 v[70:71], v[70:71], v[74:75]
	v_pk_fma_f32 v[82:83], v[114:115], v[84:85], v[82:83]
	v_lshlrev_b32_e32 v84, 16, v100
	v_and_b32_e32 v85, 0xffff0000, v100
	v_mul_f32_e32 v74, 0xbfb8aa3b, v77
	v_pk_fma_f32 v[82:83], v[118:119], v[84:85], v[82:83]
	v_exp_f32_e32 v75, v74
	v_add_f32_e32 v74, 1.0, v78
	v_mul_f32_e32 v78, 0xbfb8aa3b, v82
	v_exp_f32_e32 v78, v78
	v_mul_f32_e32 v80, 0xbfb8aa3b, v83
	v_exp_f32_e32 v80, v80
	v_add_f32_e32 v75, 1.0, v75
	s_nop 0
	v_mov_b32_dpp v88, v105 row_ror:2 row_mask:0xf bank_mask:0xf
	v_rcp_f32_e32 v74, v74
	v_rcp_f32_e32 v75, v75
	v_add_f32_e32 v78, 1.0, v78
	v_mov_b32_dpp v87, v105 row_ror:1 row_mask:0xf bank_mask:0xf
	v_mov_b32_dpp v88, v101 row_shr:2 row_mask:0xf bank_mask:0xf
	v_rcp_f32_e32 v84, v78
	v_add_f32_e32 v78, 1.0, v80
	v_mov_b32_dpp v87, v101 row_shr:1 row_mask:0xf bank_mask:0xf
	v_and_b32_e32 v79, 0xffff0000, v88
	v_rcp_f32_e32 v85, v78
	v_lshlrev_b32_e32 v78, 16, v88
	v_and_b32_e32 v81, 0xffff0000, v87
	v_lshlrev_b32_e32 v80, 16, v87
	v_pk_fma_f32 v[78:79], v[108:109], v[78:79], v[112:113]
	v_pk_mul_f32 v[74:75], v[76:77], v[74:75]
	v_lshlrev_b32_e32 v76, 16, v101
	v_and_b32_e32 v77, 0xffff0000, v101
	v_pk_fma_f32 v[78:79], v[116:117], v[80:81], v[78:79]
	v_pk_mul_f32 v[72:73], v[72:73], v[74:75]
	v_pk_fma_f32 v[76:77], v[120:121], v[76:77], v[78:79]
	v_pk_mul_f32 v[74:75], v[82:83], v[84:85]
	v_mul_f32_e32 v78, 0xbfb8aa3b, v76
	v_exp_f32_e32 v78, v78
	v_mul_f32_e32 v79, 0xbfb8aa3b, v77
	v_exp_f32_e32 v79, v79
	v_pk_mul_f32 v[74:75], v[66:67], v[74:75]
	v_add_f32_e32 v66, 1.0, v78
	v_rcp_f32_e32 v78, v66
	v_add_f32_e32 v66, 1.0, v79
	v_rcp_f32_e32 v79, v66
	v_cvt_pk_bf16_f32 v66, v70, v71
	v_add_u32_e32 v118, 0x80, v198
	v_cvt_pk_bf16_f32 v67, v72, v73
	v_pk_mul_f32 v[70:71], v[76:77], v[78:79]
	v_ashrrev_i32_e32 v119, 31, v118
	v_pk_mul_f32 v[70:71], v[68:69], v[70:71]
	v_cvt_pk_bf16_f32 v68, v74, v75
	v_cvt_pk_bf16_f32 v69, v70, v71
	global_store_dwordx4 v[152:153], v[66:69], off offset:256
	v_add_u32_e32 v120, 0x90, v198
	v_ashrrev_i32_e32 v121, 31, v120
	v_lshlrev_b64 v[66:67], 6, v[118:119]
	v_lshl_add_u64 v[66:67], v[190:191], 0, v[66:67]
	global_load_dwordx4 v[74:77], v[66:67], off
	v_lshlrev_b64 v[66:67], 6, v[120:121]
	v_add_u32_e32 v126, 0xa0, v198
	v_lshl_add_u64 v[66:67], v[190:191], 0, v[66:67]
	v_ashrrev_i32_e32 v127, 31, v126
	global_load_dwordx4 v[78:81], v[66:67], off
	v_lshlrev_b64 v[66:67], 6, v[126:127]
	v_add_u32_e32 v132, 0xb0, v198
	v_lshl_add_u64 v[66:67], v[190:191], 0, v[66:67]
	v_ashrrev_i32_e32 v133, 31, v132
	global_load_dwordx4 v[82:85], v[66:67], off
	v_lshlrev_b64 v[66:67], 6, v[132:133]
	v_lshl_add_u64 v[66:67], v[190:191], 0, v[66:67]
	global_load_dwordx4 v[86:89], v[66:67], off
	v_mad_i64_i32 v[66:67], s[2:3], v118, s89, v[200:201]
	v_mad_i64_i32 v[68:69], s[2:3], v120, s89, v[200:201]
	global_load_dwordx4 v[110:113], v[66:67], off
	global_load_dwordx4 v[90:93], v[68:69], off
	v_mad_i64_i32 v[66:67], s[2:3], v126, s89, v[200:201]
	v_mad_i64_i32 v[68:69], s[2:3], v132, s89, v[200:201]
	global_load_dwordx4 v[70:73], v[66:67], off
	s_nop 0
	global_load_dwordx4 v[66:69], v[68:69], off
	v_add_u32_e32 v117, 0x70, v198
	v_cndmask_b32_e64 v117, v118, v117, s[0:1]
	v_mad_i64_i32 v[124:125], s[2:3], v117, s89, 0
	v_lshl_add_u64 v[124:125], s[24:25], 0, v[124:125]
	v_lshl_add_u64 v[124:125], v[202:203], 1, v[124:125]
	v_and_b32_e32 v117, 0x1fcf, v118
	v_cmp_le_u32_e64 s[2:3], 16, v117
	s_mov_b64 s[4:5], exec
	s_nop 0
	s_and_b64 exec, exec, s[2:3]
	global_load_dwordx4 v[114:117], v[124:125], off
	s_mov_b64 exec, s[4:5]
	s_waitcnt vmcnt(8)
	v_mov_b32_e32 v94, v75
	v_mov_b32_e32 v95, v76
	v_mov_b32_e32 v75, v77
	v_pk_add_f32 v[74:75], v[94:95], v[74:75]
	s_waitcnt vmcnt(7)
	v_mov_b32_e32 v76, v79
	v_mov_b32_e32 v77, v80
	v_mov_b32_e32 v79, v81
	v_pk_add_f32 v[76:77], v[76:77], v[78:79]
	v_mov_b32_e32 v79, v74
	v_mov_b32_e32 v78, v76
	v_mov_b32_e32 v74, v77
	v_pk_add_f32 v[74:75], v[78:79], v[74:75]
	s_waitcnt vmcnt(6)
	v_mov_b32_e32 v78, v83
	v_mov_b32_e32 v79, v84
	v_mov_b32_e32 v83, v85
	s_waitcnt vmcnt(5)
	v_mov_b32_e32 v80, v87
	v_mov_b32_e32 v81, v88
	v_mov_b32_e32 v87, v89
	v_pk_add_f32 v[78:79], v[78:79], v[82:83]
	v_pk_add_f32 v[80:81], v[80:81], v[86:87]
	v_mov_b32_e32 v83, v78
	v_mov_b32_e32 v82, v80
	v_mov_b32_e32 v78, v81
	v_pk_add_f32 v[78:79], v[82:83], v[78:79]
	ds_bpermute_b32 v77, v1, v75
	ds_bpermute_b32 v76, v1, v74
	ds_bpermute_b32 v81, v1, v79
	ds_bpermute_b32 v80, v1, v78
	v_and_b32_e32 v1, 0x1fcf, v118
	v_cmp_gt_u32_e32 vcc, 16, v1
	s_waitcnt lgkmcnt(2)
	v_pk_add_f32 v[134:135], v[74:75], v[76:77]
	ds_bpermute_b32 v139, v199, v135
	s_waitcnt lgkmcnt(1)
	v_pk_add_f32 v[136:137], v[78:79], v[80:81]
	ds_bpermute_b32 v138, v199, v134
	ds_bpermute_b32 v141, v199, v137
	ds_bpermute_b32 v140, v199, v136
	v_mul_hi_u32_u24_e32 v123, 0x2c00, v1
	v_mul_u32_u24_e32 v122, 0x2c00, v1
	s_and_saveexec_b64 s[2:3], vcc
	s_xor_b64 s[4:5], exec, s[2:3]
	s_cbranch_execz .LBB0_1791
	v_mov_b32_e32 v117, 0
	v_mov_b32_e32 v116, 0
	v_mov_b32_e32 v115, 0
	v_mov_b32_e32 v114, 0
	s_and_saveexec_b64 s[6:7], s[0:1]
	s_cbranch_execz .LBB0_1790
	v_readlane_b32 s2, v254, 11
	v_lshlrev_b32_e32 v74, 2, v1
	v_readlane_b32 s3, v254, 12
	s_nop 4
	global_load_dword v82, v74, s[2:3]
	v_readlane_b32 s2, v254, 19
	v_readlane_b32 s3, v254, 20
	s_waitcnt vmcnt(0)
	v_fmamk_f32 v82, v82, 0x3a800000, v247
	v_lshl_add_u64 v[74:75], s[2:3], 0, v[122:123]
	v_lshl_add_u64 v[78:79], v[202:203], 2, v[74:75]
	global_load_dwordx4 v[74:77], v[78:79], off
	s_nop 0
	global_load_dwordx4 v[78:81], v[78:79], off offset:16
	v_mul_f32_e32 v83, 0x4b800000, v82
	v_cmp_gt_f32_e64 s[2:3], s90, v82
	s_nop 1
	v_cndmask_b32_e64 v82, v82, v83, s[2:3]
	v_rsq_f32_e32 v82, v82
	s_nop 0
	v_mul_f32_e32 v83, 0x45800000, v82
	v_cndmask_b32_e64 v82, v82, v83, s[2:3]
	s_waitcnt vmcnt(1)
	v_pk_mul_f32 v[74:75], v[74:75], v[82:83] op_sel_hi:[1,0]
	v_pk_mul_f32 v[76:77], v[76:77], v[82:83] op_sel_hi:[1,0]
	s_waitcnt vmcnt(0)
	v_pk_mul_f32 v[78:79], v[78:79], v[82:83] op_sel_hi:[1,0]
	v_pk_mul_f32 v[80:81], v[82:83], v[80:81] op_sel_hi:[0,1]
	v_cvt_pk_bf16_f32 v114, v74, v75
	v_cvt_pk_bf16_f32 v115, v76, v77
	v_cvt_pk_bf16_f32 v116, v78, v79
	v_cvt_pk_bf16_f32 v117, v80, v81

.LBB0_1791:
	s_or_saveexec_b64 s[2:3], s[4:5]
	v_add_u32_e32 v74, 0x70, v198
	v_cndmask_b32_e64 v74, v118, v74, s[0:1]
	v_mad_i64_i32 v[74:75], s[4:5], v74, s89, 0
	v_lshl_add_u64 v[74:75], s[24:25], 0, v[74:75]
	v_lshl_add_u64 v[124:125], v[202:203], 1, v[74:75]
	s_xor_b64 exec, exec, s[2:3]
	s_cbranch_execz .LBB0_1793


.LBB0_1881:
	s_add_u32 s56, s24, 0x100
	v_mov_b32_e32 v0, 0
	s_addc_u32 s57, s25, 0
	s_mov_b32 s58, -2
	v_mov_b32_e32 v1, v0
	v_mov_b32_e32 v2, v0
	v_mov_b32_e32 v3, v0
	v_mov_b32_e32 v4, v0
	v_mov_b32_e32 v5, v0
	v_mov_b32_e32 v6, v0
	v_mov_b32_e32 v7, v0
	v_mov_b32_e32 v16, v0
	v_mov_b32_e32 v17, v0
	v_mov_b32_e32 v18, v0
	v_mov_b32_e32 v19, v0
	v_mov_b32_e32 v20, v0
	v_mov_b32_e32 v21, v0
	v_mov_b32_e32 v22, v0
	v_mov_b32_e32 v23, v0
	v_mov_b32_e32 v32, v0
	v_mov_b32_e32 v33, v0
	v_mov_b32_e32 v34, v0
	v_mov_b32_e32 v35, v0
	s_waitcnt vmcnt(0)
	v_mov_b64_e32 v[8:9], 0
	v_mov_b64_e32 v[10:11], 0
	v_mov_b64_e32 v[12:13], 0
	v_mov_b64_e32 v[14:15], 0
	v_mov_b64_e32 v[24:25], 0
	v_mov_b64_e32 v[26:27], 0
	v_mov_b64_e32 v[28:29], 0
	v_mov_b64_e32 v[30:31], 0
	v_mov_b64_e32 v[36:37], 0
	v_mov_b64_e32 v[38:39], 0
	v_mov_b64_e32 v[40:41], 0
	v_mov_b64_e32 v[42:43], 0
	v_mov_b64_e32 v[44:45], 0
	v_mov_b64_e32 v[46:47], 0
	v_mov_b64_e32 v[48:49], 0
	v_mov_b64_e32 v[50:51], 0
	v_mov_b64_e32 v[52:53], 0
	v_mov_b64_e32 v[54:55], 0
	v_mov_b64_e32 v[56:57], 0
	v_mov_b64_e32 v[58:59], 0
	v_mov_b64_e32 v[60:61], 0
	v_mov_b64_e32 v[62:63], 0
	v_mov_b64_e32 v[64:65], 0
	v_mov_b64_e32 v[66:67], 0
	v_mov_b64_e32 v[68:69], 0
	v_mov_b64_e32 v[70:71], 0
	v_mov_b64_e32 v[72:73], 0
	v_mov_b64_e32 v[74:75], 0
	v_mov_b64_e32 v[76:77], 0
	v_mov_b64_e32 v[78:79], 0
	v_mov_b64_e32 v[80:81], 0
	v_mov_b64_e32 v[82:83], 0
	v_mov_b64_e32 v[84:85], 0
	v_mov_b64_e32 v[86:87], 0
	v_mov_b64_e32 v[88:89], 0
	v_mov_b64_e32 v[90:91], 0
	v_mov_b64_e32 v[92:93], 0
	v_mov_b64_e32 v[94:95], 0
	v_mov_b64_e32 v[96:97], 0
	v_mov_b64_e32 v[98:99], 0
	v_mov_b64_e32 v[100:101], 0
	v_mov_b64_e32 v[102:103], 0
	v_mov_b64_e32 v[104:105], 0
	v_mov_b64_e32 v[106:107], 0
	v_mov_b64_e32 v[108:109], 0
	v_mov_b64_e32 v[110:111], 0
	v_mov_b64_e32 v[112:113], 0
	v_mov_b64_e32 v[114:115], 0
	v_mov_b64_e32 v[116:117], 0
	v_mov_b64_e32 v[118:119], 0
	v_mov_b64_e32 v[120:121], 0
	v_mov_b64_e32 v[122:123], 0
	v_mov_b64_e32 v[124:125], 0
	v_mov_b64_e32 v[126:127], 0
	s_nop 0
	s_nop 0
	s_nop 0
	s_nop 0
	s_nop 0
	s_nop 0
	s_nop 0
	s_nop 0
	s_nop 0
	s_nop 0
	s_nop 0
	s_nop 0
